# v61 + seg-1 DMA addresses of the up/down K-loops via SGPR base too (offset pair provably < 2^32)
# speedup vs baseline: 1.0020x; 1.0020x over previous
; #define PG8_STAGE(bufoff, gbase, voff) do { _Pragma("unroll") for (int _i = 0; _i < 2; ++_i) \
;         __builtin_amdgcn_global_load_lds((const unsigned*)((const char*)(gbase) + (voff)[_i]), (PG8_LAS unsigned*)(lds + (bufoff) + ldsw + _i * 8192), 16, 0, 0); } while (0)
; #define PG8_LDA(dst, b, h) do { _Pragma("unroll") for (int m = 0; m < 4; ++m) _Pragma("unroll") for (int k = 0; k < 2; ++k) dst[m][k] = *(const PG8_LAS bf16x8*)(lds + PG8_SA(b, h) + aoff + m * 2048 + k * 1024); } while (0)
; #define PG8_LDB(dst, b, h) do { _Pragma("unroll") for (int n = 0; n < 2; ++n) _Pragma("unroll") for (int k = 0; k < 2; ++k) dst[n][k] = *(const PG8_LAS bf16x8*)(lds + PG8_SB(b, h) + boff + n * 2048 + k * 1024); } while (0)
; #define PG8_MMA(ai, bj, At, Bt) do { __builtin_amdgcn_s_setprio(1); _Pragma("unroll") for (int m = 0; m < 4; ++m) _Pragma("unroll") for (int n = 0; n < 2; ++n) _Pragma("unroll") for (int k = 0; k < 2; ++k) \
;         acc[ai][bj][m][n] = __builtin_amdgcn_mfma_f32_16x16x32_bf16(Bt[n][k], At[m][k], acc[ai][bj][m][n], 0, 0, 0); __builtin_amdgcn_s_setprio(0); } while (0)
; #define PG8_WAIT_V(n) asm volatile("s_waitcnt vmcnt(" #n ")" ::: "memory")
; #define PG8_WAIT_L(n) asm volatile("s_waitcnt lgkmcnt(" #n ")" ::: "memory")
; template <class Epi, class Sched, bool ALIGN_EPI = false, bool SP2 = false>
; __device__ __forceinline__ void gemm_phase(PG8_LAS unsigned char* lds, const Gemm g, const Sched& S, const Epi& E, const int wv) {
;     ...
;             const bool last = (t == nt - 2);
;             const char* a1 = cA + (size_t)(t + 1) * kstep;
;             const char* a2 = last ? nA : cA + (size_t)(t + 2) * kstep; const char* b2 = last ? nB : cB + (size_t)(t + 2) * kstep;
;             const char* a3 = a2 + kstep; const char* b3 = b2 + kstep;
;             if (last && has_next) S.a_ready(nxt);
;             if constexpr (SP2) {
;             PG8_LDB(B0, 0, 0); PG8_LDB(B1, 0, 1); PG8_SCHED; PG8_LDA(At, 0, 0); PG8_STAGE(PG8_SA(1, 1), a1 + hstepA, voffA);
;             PG8_WAIT_V(8); PG8_WAIT_L(0); PG8_BAR; PG8_MMA(0, 0, At, B0); PG8_MMA(0, 1, At, B1); PG8_BAR; PG8_SCHED;
;             PG8_LDA(At, 0, 1); PG8_STAGE(PG8_SB(0, 0), b2, voffB); PG8_STAGE(PG8_SB(0, 1), b2 + hstepB, voffB); PG8_STAGE(PG8_SA(0, 0), a2, voffA);
;             PG8_WAIT_V(8); PG8_WAIT_L(0); PG8_BAR; PG8_MMA(1, 0, At, B0); PG8_MMA(1, 1, At, B1); PG8_BAR; PG8_SCHED;
.LBB0_809:
	s_add_i32 s52, s46, 2
	s_add_u32 s14, s48, 0x100
	s_addc_u32 s15, s49, 0
	s_add_i32 s53, 0, 0x10000
	s_cmp_eq_u32 s71, s46
	s_cselect_b32 s47, s11, s15
	s_cselect_b32 s46, s13, s14
	s_cselect_b32 s77, s87, s51
	s_cselect_b32 s76, s86, s35
	s_add_i32 s75, 0, 0x14000
	v_add_u32_e32 v150, s53, v208
	v_add_u32_e32 v166, s75, v208
	ds_read_b128 v[138:141], v150
	ds_read_b128 v[142:145], v150 offset:1024
	ds_read_b128 v[146:149], v150 offset:2048
	ds_read_b128 v[150:153], v150 offset:3072
	ds_read_b128 v[154:157], v166
	ds_read_b128 v[158:161], v166 offset:1024
	ds_read_b128 v[162:165], v166 offset:2048
	ds_read_b128 v[166:169], v166 offset:3072
	s_add_i32 m0, s63, 0xc000
	ds_read_b128 v[194:197], v211
	ds_read_b128 v[198:201], v211 offset:1024
	ds_read_b128 v[202:205], v211 offset:2048
	ds_read_b128 v[214:217], v211 offset:3072
	ds_read_b128 v[228:231], v211 offset:4096
	ds_read_b128 v[232:235], v211 offset:5120
	ds_read_b128 v[236:239], v211 offset:6144
	ds_read_b128 v[240:243], v211 offset:7168
	global_load_lds_dwordx4 v182, s[48:49]
	v_lshl_add_u64 v[190:191], s[48:49], 0, v[184:185]
	s_add_i32 m0, s63, 0xe000
	s_nop 0
	global_load_lds_dwordx4 v[190:191], off
	s_waitcnt vmcnt(8)
	s_waitcnt lgkmcnt(0)
	s_barrier
	v_mfma_f32_16x16x32_bf16 v[118:121], v[138:141], v[194:197], v[118:121]
	v_mfma_f32_16x16x32_bf16 v[46:49], v[146:149], v[194:197], v[46:49]
	v_mfma_f32_16x16x32_bf16 v[110:113], v[138:141], v[202:205], v[110:113]
	v_mfma_f32_16x16x32_bf16 v[38:41], v[146:149], v[202:205], v[38:41]
	v_mfma_f32_16x16x32_bf16 v[134:137], v[138:141], v[228:231], v[134:137]
	v_mfma_f32_16x16x32_bf16 v[62:65], v[146:149], v[228:231], v[62:65]
	v_mfma_f32_16x16x32_bf16 v[130:133], v[138:141], v[236:239], v[130:133]
	v_mfma_f32_16x16x32_bf16 v[58:61], v[146:149], v[236:239], v[58:61]
	v_mfma_f32_16x16x32_bf16 v[118:121], v[142:145], v[198:201], v[118:121]
	v_mfma_f32_16x16x32_bf16 v[46:49], v[150:153], v[198:201], v[46:49]
	v_mfma_f32_16x16x32_bf16 v[110:113], v[142:145], v[214:217], v[110:113]
	v_mfma_f32_16x16x32_bf16 v[38:41], v[150:153], v[214:217], v[38:41]
	v_mfma_f32_16x16x32_bf16 v[134:137], v[142:145], v[232:235], v[134:137]
	v_mfma_f32_16x16x32_bf16 v[62:65], v[150:153], v[232:235], v[62:65]
	v_mfma_f32_16x16x32_bf16 v[130:133], v[142:145], v[240:243], v[130:133]
	v_mfma_f32_16x16x32_bf16 v[58:61], v[150:153], v[240:243], v[58:61]
	v_mfma_f32_16x16x32_bf16 v[114:117], v[154:157], v[194:197], v[114:117]
	v_mfma_f32_16x16x32_bf16 v[42:45], v[162:165], v[194:197], v[42:45]
	v_mfma_f32_16x16x32_bf16 v[106:109], v[154:157], v[202:205], v[106:109]
	v_mfma_f32_16x16x32_bf16 v[34:37], v[162:165], v[202:205], v[34:37]
	v_mfma_f32_16x16x32_bf16 v[126:129], v[154:157], v[228:231], v[126:129]
	v_mfma_f32_16x16x32_bf16 v[54:57], v[162:165], v[228:231], v[54:57]
	v_mfma_f32_16x16x32_bf16 v[122:125], v[154:157], v[236:239], v[122:125]
	v_mfma_f32_16x16x32_bf16 v[50:53], v[162:165], v[236:239], v[50:53]
	v_mfma_f32_16x16x32_bf16 v[114:117], v[158:161], v[198:201], v[114:117]
	v_mfma_f32_16x16x32_bf16 v[42:45], v[166:169], v[198:201], v[42:45]
	v_mfma_f32_16x16x32_bf16 v[106:109], v[158:161], v[214:217], v[106:109]
	v_mfma_f32_16x16x32_bf16 v[34:37], v[166:169], v[214:217], v[34:37]
	v_mfma_f32_16x16x32_bf16 v[126:129], v[158:161], v[232:235], v[126:129]
	v_mfma_f32_16x16x32_bf16 v[54:57], v[166:169], v[232:235], v[54:57]
	v_mfma_f32_16x16x32_bf16 v[122:125], v[158:161], v[240:243], v[122:125]
	v_mfma_f32_16x16x32_bf16 v[50:53], v[166:169], v[240:243], v[50:53]
	s_barrier
	s_add_i32 s48, s53, s62
	s_mov_b32 m0, s48
	ds_read_b128 v[194:197], v211 offset:16384
	ds_read_b128 v[198:201], v211 offset:17408
	ds_read_b128 v[202:205], v211 offset:18432
	ds_read_b128 v[214:217], v211 offset:19456
	ds_read_b128 v[228:231], v211 offset:20480
	ds_read_b128 v[232:235], v211 offset:21504
	ds_read_b128 v[236:239], v211 offset:22528
	ds_read_b128 v[240:243], v211 offset:23552
	global_load_lds_dwordx4 v0, s[76:77]
	s_add_i32 m0, s48, 0x2000
	s_add_u32 s48, s76, s16
	s_addc_u32 s49, s77, s17
	s_add_i32 s53, s75, s62
	global_load_lds_dwordx4 v174, s[76:77]
	v_lshl_add_u64 v[218:219], s[48:49], 0, v[0:1]
	s_mov_b32 m0, s53
	v_lshl_add_u64 v[244:245], s[48:49], 0, v[174:175]
	global_load_lds_dwordx4 v[218:219], off
	s_add_i32 m0, s53, 0x2000
	v_lshl_add_u64 v[246:247], s[46:47], 0, v[170:171]
	global_load_lds_dwordx4 v[244:245], off
	s_mov_b32 m0, s63
	v_lshl_add_u64 v[248:249], s[46:47], 0, v[172:173]
	global_load_lds_dwordx4 v[246:247], off
	s_mov_b32 m0, s64
	s_nop 0
	global_load_lds_dwordx4 v[248:249], off
	s_waitcnt vmcnt(8)
	s_waitcnt lgkmcnt(0)
	s_barrier
; #define PG8_STAGE(bufoff, gbase, voff) do { _Pragma("unroll") for (int _i = 0; _i < 2; ++_i) \
;         __builtin_amdgcn_global_load_lds((const unsigned*)((const char*)(gbase) + (voff)[_i]), (PG8_LAS unsigned*)(lds + (bufoff) + ldsw + _i * 8192), 16, 0, 0); } while (0)
; #define PG8_LDA(dst, b, h) do { _Pragma("unroll") for (int m = 0; m < 4; ++m) _Pragma("unroll") for (int k = 0; k < 2; ++k) dst[m][k] = *(const PG8_LAS bf16x8*)(lds + PG8_SA(b, h) + aoff + m * 2048 + k * 1024); } while (0)
; #define PG8_LDB(dst, b, h) do { _Pragma("unroll") for (int n = 0; n < 2; ++n) _Pragma("unroll") for (int k = 0; k < 2; ++k) dst[n][k] = *(const PG8_LAS bf16x8*)(lds + PG8_SB(b, h) + boff + n * 2048 + k * 1024); } while (0)
; #define PG8_MMA(ai, bj, At, Bt) do { __builtin_amdgcn_s_setprio(1); _Pragma("unroll") for (int m = 0; m < 4; ++m) _Pragma("unroll") for (int n = 0; n < 2; ++n) _Pragma("unroll") for (int k = 0; k < 2; ++k) \
;         acc[ai][bj][m][n] = __builtin_amdgcn_mfma_f32_16x16x32_bf16(Bt[n][k], At[m][k], acc[ai][bj][m][n], 0, 0, 0); __builtin_amdgcn_s_setprio(0); } while (0)
; #define PG8_WAIT_V(n) asm volatile("s_waitcnt vmcnt(" #n ")" ::: "memory")
; #define PG8_WAIT_L(n) asm volatile("s_waitcnt lgkmcnt(" #n ")" ::: "memory")
; #define PG8_BAR __builtin_amdgcn_s_barrier()
; #define PG8_SCHED __builtin_amdgcn_sched_barrier(0)
; template <class Epi, class Sched, bool ALIGN_EPI = false, bool SP2 = false>
; __device__ __forceinline__ void gemm_phase(PG8_LAS unsigned char* lds, const Gemm g, const Sched& S, const Epi& E, const int wv) {
;     ...
;             PG8_WAIT_V(8); PG8_WAIT_L(0); PG8_BAR; PG8_MMA(1, 0, At, B0); PG8_MMA(1, 1, At, B1); PG8_BAR; PG8_SCHED;
;             PG8_LDB(B0, 1, 0); PG8_LDB(B1, 1, 1); PG8_SCHED; PG8_LDA(At, 1, 0); PG8_STAGE(PG8_SA(0, 1), a2 + hstepA, voffA);
;             PG8_WAIT_V(8); PG8_WAIT_L(0); PG8_BAR; PG8_MMA(0, 0, At, B0); PG8_MMA(0, 1, At, B1); PG8_BAR; PG8_SCHED;
	v_mfma_f32_16x16x32_bf16 v[86:89], v[138:141], v[194:197], v[86:89]
	v_mfma_f32_16x16x32_bf16 v[14:17], v[146:149], v[194:197], v[14:17]
	v_mfma_f32_16x16x32_bf16 v[70:73], v[138:141], v[202:205], v[70:73]
	v_mfma_f32_16x16x32_bf16 v[6:9], v[146:149], v[202:205], v[6:9]
	v_mfma_f32_16x16x32_bf16 v[102:105], v[138:141], v[228:231], v[102:105]
	v_mfma_f32_16x16x32_bf16 v[30:33], v[146:149], v[228:231], v[30:33]
	v_mfma_f32_16x16x32_bf16 v[98:101], v[138:141], v[236:239], v[98:101]
	v_mfma_f32_16x16x32_bf16 v[26:29], v[146:149], v[236:239], v[26:29]
	v_mfma_f32_16x16x32_bf16 v[86:89], v[142:145], v[198:201], v[86:89]
	v_mfma_f32_16x16x32_bf16 v[14:17], v[150:153], v[198:201], v[14:17]
	v_mfma_f32_16x16x32_bf16 v[70:73], v[142:145], v[214:217], v[70:73]
	v_mfma_f32_16x16x32_bf16 v[6:9], v[150:153], v[214:217], v[6:9]
	v_mfma_f32_16x16x32_bf16 v[102:105], v[142:145], v[232:235], v[102:105]
	v_mfma_f32_16x16x32_bf16 v[30:33], v[150:153], v[232:235], v[30:33]
	v_mfma_f32_16x16x32_bf16 v[98:101], v[142:145], v[240:243], v[98:101]
	v_mfma_f32_16x16x32_bf16 v[26:29], v[150:153], v[240:243], v[26:29]
	v_mfma_f32_16x16x32_bf16 v[82:85], v[154:157], v[194:197], v[82:85]
	v_mfma_f32_16x16x32_bf16 v[10:13], v[162:165], v[194:197], v[10:13]
	v_mfma_f32_16x16x32_bf16 v[66:69], v[154:157], v[202:205], v[66:69]
	v_mfma_f32_16x16x32_bf16 v[2:5], v[162:165], v[202:205], v[2:5]
	v_mfma_f32_16x16x32_bf16 v[94:97], v[154:157], v[228:231], v[94:97]
	v_mfma_f32_16x16x32_bf16 v[22:25], v[162:165], v[228:231], v[22:25]
	v_mfma_f32_16x16x32_bf16 v[90:93], v[154:157], v[236:239], v[90:93]
	v_mfma_f32_16x16x32_bf16 v[18:21], v[162:165], v[236:239], v[18:21]
	v_mfma_f32_16x16x32_bf16 v[82:85], v[158:161], v[198:201], v[82:85]
	v_mfma_f32_16x16x32_bf16 v[10:13], v[166:169], v[198:201], v[10:13]
	v_mfma_f32_16x16x32_bf16 v[66:69], v[158:161], v[214:217], v[66:69]
	v_mfma_f32_16x16x32_bf16 v[2:5], v[166:169], v[214:217], v[2:5]
	v_mfma_f32_16x16x32_bf16 v[94:97], v[158:161], v[232:235], v[94:97]
	v_mfma_f32_16x16x32_bf16 v[22:25], v[166:169], v[232:235], v[22:25]
	v_mfma_f32_16x16x32_bf16 v[90:93], v[158:161], v[240:243], v[90:93]
	v_mfma_f32_16x16x32_bf16 v[18:21], v[166:169], v[240:243], v[18:21]
	s_barrier
	s_add_i32 s48, 0, 0x18000
	s_add_i32 s49, 0, 0x1c000
	v_add_u32_e32 v150, s48, v208
	v_add_u32_e32 v166, s49, v208
	ds_read_b128 v[138:141], v150
	ds_read_b128 v[142:145], v150 offset:1024
	ds_read_b128 v[146:149], v150 offset:2048
	ds_read_b128 v[150:153], v150 offset:3072
	ds_read_b128 v[154:157], v166
	ds_read_b128 v[158:161], v166 offset:1024
	ds_read_b128 v[162:165], v166 offset:2048
	ds_read_b128 v[166:169], v166 offset:3072
	s_add_u32 s46, s46, 0x80000
	s_addc_u32 s47, s47, 0
	s_mov_b32 m0, s65
	ds_read_b128 v[194:197], v211 offset:32768
	ds_read_b128 v[198:201], v211 offset:33792
	ds_read_b128 v[202:205], v211 offset:34816
	ds_read_b128 v[214:217], v211 offset:35840
	ds_read_b128 v[228:231], v211 offset:36864
	ds_read_b128 v[232:235], v211 offset:37888
	ds_read_b128 v[236:239], v211 offset:38912
	ds_read_b128 v[240:243], v211 offset:39936
	global_load_lds_dwordx4 v170, s[46:47]
	s_mov_b32 m0, s66
	s_nop 0
	global_load_lds_dwordx4 v172, s[46:47]
	s_waitcnt vmcnt(8)
	s_waitcnt lgkmcnt(0)
	s_barrier
	v_mfma_f32_16x16x32_bf16 v[118:121], v[138:141], v[194:197], v[118:121]
	v_mfma_f32_16x16x32_bf16 v[46:49], v[146:149], v[194:197], v[46:49]
	v_mfma_f32_16x16x32_bf16 v[110:113], v[138:141], v[202:205], v[110:113]
	v_mfma_f32_16x16x32_bf16 v[38:41], v[146:149], v[202:205], v[38:41]
	v_mfma_f32_16x16x32_bf16 v[134:137], v[138:141], v[228:231], v[134:137]
	v_mfma_f32_16x16x32_bf16 v[62:65], v[146:149], v[228:231], v[62:65]
	v_mfma_f32_16x16x32_bf16 v[130:133], v[138:141], v[236:239], v[130:133]
	v_mfma_f32_16x16x32_bf16 v[58:61], v[146:149], v[236:239], v[58:61]
	v_mfma_f32_16x16x32_bf16 v[118:121], v[142:145], v[198:201], v[118:121]
	v_mfma_f32_16x16x32_bf16 v[46:49], v[150:153], v[198:201], v[46:49]
	v_mfma_f32_16x16x32_bf16 v[110:113], v[142:145], v[214:217], v[110:113]
	v_mfma_f32_16x16x32_bf16 v[38:41], v[150:153], v[214:217], v[38:41]
	v_mfma_f32_16x16x32_bf16 v[134:137], v[142:145], v[232:235], v[134:137]
	v_mfma_f32_16x16x32_bf16 v[62:65], v[150:153], v[232:235], v[62:65]
	v_mfma_f32_16x16x32_bf16 v[130:133], v[142:145], v[240:243], v[130:133]
	v_mfma_f32_16x16x32_bf16 v[58:61], v[150:153], v[240:243], v[58:61]
	v_mfma_f32_16x16x32_bf16 v[114:117], v[154:157], v[194:197], v[114:117]
	v_mfma_f32_16x16x32_bf16 v[42:45], v[162:165], v[194:197], v[42:45]
	v_mfma_f32_16x16x32_bf16 v[106:109], v[154:157], v[202:205], v[106:109]
	v_mfma_f32_16x16x32_bf16 v[34:37], v[162:165], v[202:205], v[34:37]
	v_mfma_f32_16x16x32_bf16 v[126:129], v[154:157], v[228:231], v[126:129]
	v_mfma_f32_16x16x32_bf16 v[54:57], v[162:165], v[228:231], v[54:57]
	v_mfma_f32_16x16x32_bf16 v[122:125], v[154:157], v[236:239], v[122:125]
	v_mfma_f32_16x16x32_bf16 v[50:53], v[162:165], v[236:239], v[50:53]
	v_mfma_f32_16x16x32_bf16 v[114:117], v[158:161], v[198:201], v[114:117]
	v_mfma_f32_16x16x32_bf16 v[42:45], v[166:169], v[198:201], v[42:45]
	v_mfma_f32_16x16x32_bf16 v[106:109], v[158:161], v[214:217], v[106:109]
	v_mfma_f32_16x16x32_bf16 v[34:37], v[166:169], v[214:217], v[34:37]
	v_mfma_f32_16x16x32_bf16 v[126:129], v[158:161], v[232:235], v[126:129]
	v_mfma_f32_16x16x32_bf16 v[54:57], v[166:169], v[232:235], v[54:57]
	v_mfma_f32_16x16x32_bf16 v[122:125], v[158:161], v[240:243], v[122:125]
	v_mfma_f32_16x16x32_bf16 v[50:53], v[166:169], v[240:243], v[50:53]
	s_barrier
; #define PG8_STAGE(bufoff, gbase, voff) do { _Pragma("unroll") for (int _i = 0; _i < 2; ++_i) \
;         __builtin_amdgcn_global_load_lds((const unsigned*)((const char*)(gbase) + (voff)[_i]), (PG8_LAS unsigned*)(lds + (bufoff) + ldsw + _i * 8192), 16, 0, 0); } while (0)
; #define PG8_LDA(dst, b, h) do { _Pragma("unroll") for (int m = 0; m < 4; ++m) _Pragma("unroll") for (int k = 0; k < 2; ++k) dst[m][k] = *(const PG8_LAS bf16x8*)(lds + PG8_SA(b, h) + aoff + m * 2048 + k * 1024); } while (0)
; #define PG8_MMA(ai, bj, At, Bt) do { __builtin_amdgcn_s_setprio(1); _Pragma("unroll") for (int m = 0; m < 4; ++m) _Pragma("unroll") for (int n = 0; n < 2; ++n) _Pragma("unroll") for (int k = 0; k < 2; ++k) \
;         acc[ai][bj][m][n] = __builtin_amdgcn_mfma_f32_16x16x32_bf16(Bt[n][k], At[m][k], acc[ai][bj][m][n], 0, 0, 0); __builtin_amdgcn_s_setprio(0); } while (0)
; #define PG8_WAIT_V(n) asm volatile("s_waitcnt vmcnt(" #n ")" ::: "memory")
; #define PG8_WAIT_L(n) asm volatile("s_waitcnt lgkmcnt(" #n ")" ::: "memory")
; #define PG8_BAR __builtin_amdgcn_s_barrier()
; #define PG8_SCHED __builtin_amdgcn_sched_barrier(0)
; template <class Epi, class Sched, bool ALIGN_EPI = false, bool SP2 = false>
; __device__ __forceinline__ void gemm_phase(PG8_LAS unsigned char* lds, const Gemm g, const Sched& S, const Epi& E, const int wv) {
;     ...
;             PG8_LDA(At, 1, 1); PG8_STAGE(PG8_SB(1, 0), b3, voffB); PG8_STAGE(PG8_SB(1, 1), b3 + hstepB, voffB); PG8_STAGE(PG8_SA(1, 0), a3, voffA);
;             PG8_WAIT_V(8); PG8_WAIT_L(0); PG8_BAR; PG8_MMA(1, 0, At, B0); PG8_MMA(1, 1, At, B1); PG8_BAR; PG8_SCHED;
	s_add_i32 s46, s48, s62
	s_add_i32 m0, s46, 0xffffff80
	ds_read_b128 v[194:197], v211 offset:49152
	ds_read_b128 v[198:201], v211 offset:50176
	ds_read_b128 v[202:205], v211 offset:51200
	ds_read_b128 v[214:217], v211 offset:52224
	ds_read_b128 v[228:231], v211 offset:53248
	ds_read_b128 v[232:235], v211 offset:54272
	ds_read_b128 v[236:239], v211 offset:55296
	ds_read_b128 v[240:243], v211 offset:56320
	global_load_lds_dwordx4 v0, s[76:77] offset:128
	s_add_i32 m0, s46, 0x1f80
	s_add_i32 s46, s49, s62
	global_load_lds_dwordx4 v174, s[76:77] offset:128
	s_add_i32 m0, s46, 0xffffff80
	s_nop 0
	global_load_lds_dwordx4 v[218:219], off offset:128
	s_add_i32 m0, s46, 0x1f80
	s_nop 0
	global_load_lds_dwordx4 v[244:245], off offset:128
	s_add_i32 m0, s69, 0xffffff80
	s_nop 0
	global_load_lds_dwordx4 v[246:247], off offset:128
	s_add_i32 m0, s70, 0xffffff80
	s_nop 0
	global_load_lds_dwordx4 v[248:249], off offset:128
	s_waitcnt vmcnt(8)
	s_waitcnt lgkmcnt(0)
	s_barrier
	v_mfma_f32_16x16x32_bf16 v[86:89], v[138:141], v[194:197], v[86:89]
	v_mfma_f32_16x16x32_bf16 v[14:17], v[146:149], v[194:197], v[14:17]
	v_mfma_f32_16x16x32_bf16 v[70:73], v[138:141], v[202:205], v[70:73]
	v_mfma_f32_16x16x32_bf16 v[6:9], v[146:149], v[202:205], v[6:9]
	v_mfma_f32_16x16x32_bf16 v[102:105], v[138:141], v[228:231], v[102:105]
	v_mfma_f32_16x16x32_bf16 v[30:33], v[146:149], v[228:231], v[30:33]
	v_mfma_f32_16x16x32_bf16 v[98:101], v[138:141], v[236:239], v[98:101]
	v_mfma_f32_16x16x32_bf16 v[26:29], v[146:149], v[236:239], v[26:29]
	v_mfma_f32_16x16x32_bf16 v[86:89], v[142:145], v[198:201], v[86:89]
	v_mfma_f32_16x16x32_bf16 v[14:17], v[150:153], v[198:201], v[14:17]
	v_mfma_f32_16x16x32_bf16 v[70:73], v[142:145], v[214:217], v[70:73]
	v_mfma_f32_16x16x32_bf16 v[6:9], v[150:153], v[214:217], v[6:9]
	v_mfma_f32_16x16x32_bf16 v[102:105], v[142:145], v[232:235], v[102:105]
	v_mfma_f32_16x16x32_bf16 v[30:33], v[150:153], v[232:235], v[30:33]
	v_mfma_f32_16x16x32_bf16 v[98:101], v[142:145], v[240:243], v[98:101]
	v_mfma_f32_16x16x32_bf16 v[26:29], v[150:153], v[240:243], v[26:29]
	v_mfma_f32_16x16x32_bf16 v[82:85], v[154:157], v[194:197], v[82:85]
	v_mfma_f32_16x16x32_bf16 v[10:13], v[162:165], v[194:197], v[10:13]
	v_mfma_f32_16x16x32_bf16 v[66:69], v[154:157], v[202:205], v[66:69]
	v_mfma_f32_16x16x32_bf16 v[2:5], v[162:165], v[202:205], v[2:5]
	v_mfma_f32_16x16x32_bf16 v[94:97], v[154:157], v[228:231], v[94:97]
	v_mfma_f32_16x16x32_bf16 v[22:25], v[162:165], v[228:231], v[22:25]
	v_mfma_f32_16x16x32_bf16 v[90:93], v[154:157], v[236:239], v[90:93]
	v_mfma_f32_16x16x32_bf16 v[18:21], v[162:165], v[236:239], v[18:21]
	v_mfma_f32_16x16x32_bf16 v[82:85], v[158:161], v[198:201], v[82:85]
	v_mfma_f32_16x16x32_bf16 v[10:13], v[166:169], v[198:201], v[10:13]
	v_mfma_f32_16x16x32_bf16 v[66:69], v[158:161], v[214:217], v[66:69]
	v_mfma_f32_16x16x32_bf16 v[2:5], v[166:169], v[214:217], v[2:5]
	v_mfma_f32_16x16x32_bf16 v[94:97], v[158:161], v[232:235], v[94:97]
	v_mfma_f32_16x16x32_bf16 v[22:25], v[166:169], v[232:235], v[22:25]
	v_mfma_f32_16x16x32_bf16 v[90:93], v[158:161], v[240:243], v[90:93]
	v_mfma_f32_16x16x32_bf16 v[18:21], v[166:169], v[240:243], v[18:21]
	s_barrier
	s_add_u32 s35, s35, 0x100
	s_addc_u32 s51, s51, 0
	s_cmp_ge_i32 s52, s67
	s_mov_b64 s[48:49], s[14:15]
	s_mov_b32 s46, s52
	s_cbranch_scc0 .LBB0_809
	s_movk_i32 s75, 0x2000
	s_movk_i32 s76, 0x3000
	s_and_b64 vcc, exec, s[30:31]
	s_cbranch_vccz .LBB0_784

; #define PG8_STAGE(bufoff, gbase, voff) do { _Pragma("unroll") for (int _i = 0; _i < 2; ++_i) \
;         __builtin_amdgcn_global_load_lds((const unsigned*)((const char*)(gbase) + (voff)[_i]), (PG8_LAS unsigned*)(lds + (bufoff) + ldsw + _i * 8192), 16, 0, 0); } while (0)
; #define PG8_LDA(dst, b, h) do { _Pragma("unroll") for (int m = 0; m < 4; ++m) _Pragma("unroll") for (int k = 0; k < 2; ++k) dst[m][k] = *(const PG8_LAS bf16x8*)(lds + PG8_SA(b, h) + aoff + m * 2048 + k * 1024); } while (0)
; #define PG8_LDB(dst, b, h) do { _Pragma("unroll") for (int n = 0; n < 2; ++n) _Pragma("unroll") for (int k = 0; k < 2; ++k) dst[n][k] = *(const PG8_LAS bf16x8*)(lds + PG8_SB(b, h) + boff + n * 2048 + k * 1024); } while (0)
; #define PG8_MMA(ai, bj, At, Bt) do { __builtin_amdgcn_s_setprio(1); _Pragma("unroll") for (int m = 0; m < 4; ++m) _Pragma("unroll") for (int n = 0; n < 2; ++n) _Pragma("unroll") for (int k = 0; k < 2; ++k) \
;         acc[ai][bj][m][n] = __builtin_amdgcn_mfma_f32_16x16x32_bf16(Bt[n][k], At[m][k], acc[ai][bj][m][n], 0, 0, 0); __builtin_amdgcn_s_setprio(0); } while (0)
; #define PG8_WAIT_V(n) asm volatile("s_waitcnt vmcnt(" #n ")" ::: "memory")
; #define PG8_WAIT_L(n) asm volatile("s_waitcnt lgkmcnt(" #n ")" ::: "memory")
; template <class Epi, class Sched, bool ALIGN_EPI = false, bool SP2 = false>
; __device__ __forceinline__ void gemm_phase(PG8_LAS unsigned char* lds, const Gemm g, const Sched& S, const Epi& E, const int wv) {
;     ...
;             const bool last = (t == nt - 2);
;             const char* a1 = cA + (size_t)(t + 1) * kstep;
;             const char* a2 = last ? nA : cA + (size_t)(t + 2) * kstep; const char* b2 = last ? nB : cB + (size_t)(t + 2) * kstep;
;             const char* a3 = a2 + kstep; const char* b3 = b2 + kstep;
;             if (last && has_next) S.a_ready(nxt);
;             if constexpr (SP2) {
;             PG8_LDB(B0, 0, 0); PG8_LDB(B1, 0, 1); PG8_SCHED; PG8_LDA(At, 0, 0); PG8_STAGE(PG8_SA(1, 1), a1 + hstepA, voffA);
;             PG8_WAIT_V(8); PG8_WAIT_L(0); PG8_BAR; PG8_MMA(0, 0, At, B0); PG8_MMA(0, 1, At, B1); PG8_BAR; PG8_SCHED;
;             PG8_LDA(At, 0, 1); PG8_STAGE(PG8_SB(0, 0), b2, voffB); PG8_STAGE(PG8_SB(0, 1), b2 + hstepB, voffB); PG8_STAGE(PG8_SA(0, 0), a2, voffA);
;             PG8_WAIT_V(8); PG8_WAIT_L(0); PG8_BAR; PG8_MMA(1, 0, At, B0); PG8_MMA(1, 1, At, B1); PG8_BAR; PG8_SCHED;
.LBB0_990:
	s_add_i32 s67, s44, 2
	s_add_u32 s34, s30, 0x100
	s_addc_u32 s35, s31, 0
	s_add_i32 s70, 0, 0x10000
	s_cmp_eq_u32 s59, s44
	s_cselect_b32 s45, s13, s35
	s_cselect_b32 s44, s12, s34
	s_cselect_b32 s69, s15, s66
	s_cselect_b32 s68, s14, s65
	s_add_i32 s71, 0, 0x14000
	v_add_u32_e32 v142, s70, v230
	v_add_u32_e32 v158, s71, v230
	ds_read_b128 v[114:117], v142
	ds_read_b128 v[126:129], v142 offset:1024
	ds_read_b128 v[138:141], v142 offset:2048
	ds_read_b128 v[142:145], v142 offset:3072
	ds_read_b128 v[146:149], v158
	ds_read_b128 v[150:153], v158 offset:1024
	ds_read_b128 v[154:157], v158 offset:2048
	ds_read_b128 v[158:161], v158 offset:3072
	s_add_i32 m0, s52, 0xc000
	ds_read_b128 v[162:165], v235
	ds_read_b128 v[166:169], v235 offset:1024
	ds_read_b128 v[170:173], v235 offset:2048
	ds_read_b128 v[174:177], v235 offset:3072
	ds_read_b128 v[178:181], v235 offset:4096
	ds_read_b128 v[182:185], v235 offset:5120
	ds_read_b128 v[204:207], v235 offset:6144
	ds_read_b128 v[208:211], v235 offset:7168
	global_load_lds_dwordx4 v200, s[30:31]
	s_add_i32 m0, s52, 0xe000
	s_nop 0
	global_load_lds_dwordx4 v202, s[30:31]
	s_waitcnt vmcnt(8)
	s_waitcnt lgkmcnt(0)
	s_barrier
	v_mfma_f32_16x16x32_bf16 v[134:137], v[114:117], v[162:165], v[134:137]
	v_mfma_f32_16x16x32_bf16 v[130:133], v[138:141], v[162:165], v[130:133]
	v_mfma_f32_16x16x32_bf16 v[110:113], v[114:117], v[170:173], v[110:113]
	v_mfma_f32_16x16x32_bf16 v[106:109], v[138:141], v[170:173], v[106:109]
	v_mfma_f32_16x16x32_bf16 v[94:97], v[114:117], v[178:181], v[94:97]
	v_mfma_f32_16x16x32_bf16 v[90:93], v[138:141], v[178:181], v[90:93]
	v_mfma_f32_16x16x32_bf16 v[78:81], v[114:117], v[204:207], v[78:81]
	v_mfma_f32_16x16x32_bf16 v[74:77], v[138:141], v[204:207], v[74:77]
	v_mfma_f32_16x16x32_bf16 v[134:137], v[126:129], v[166:169], v[134:137]
	v_mfma_f32_16x16x32_bf16 v[130:133], v[142:145], v[166:169], v[130:133]
	v_mfma_f32_16x16x32_bf16 v[110:113], v[126:129], v[174:177], v[110:113]
	v_mfma_f32_16x16x32_bf16 v[106:109], v[142:145], v[174:177], v[106:109]
	v_mfma_f32_16x16x32_bf16 v[94:97], v[126:129], v[182:185], v[94:97]
	v_mfma_f32_16x16x32_bf16 v[90:93], v[142:145], v[182:185], v[90:93]
	v_mfma_f32_16x16x32_bf16 v[78:81], v[126:129], v[208:211], v[78:81]
	v_mfma_f32_16x16x32_bf16 v[74:77], v[142:145], v[208:211], v[74:77]
	v_mfma_f32_16x16x32_bf16 v[122:125], v[146:149], v[162:165], v[122:125]
	v_mfma_f32_16x16x32_bf16 v[118:121], v[154:157], v[162:165], v[118:121]
	v_mfma_f32_16x16x32_bf16 v[102:105], v[146:149], v[170:173], v[102:105]
	v_mfma_f32_16x16x32_bf16 v[98:101], v[154:157], v[170:173], v[98:101]
	v_mfma_f32_16x16x32_bf16 v[86:89], v[146:149], v[178:181], v[86:89]
	v_mfma_f32_16x16x32_bf16 v[82:85], v[154:157], v[178:181], v[82:85]
	v_mfma_f32_16x16x32_bf16 v[70:73], v[146:149], v[204:207], v[70:73]
	v_mfma_f32_16x16x32_bf16 v[66:69], v[154:157], v[204:207], v[66:69]
	v_mfma_f32_16x16x32_bf16 v[122:125], v[150:153], v[166:169], v[122:125]
	v_mfma_f32_16x16x32_bf16 v[118:121], v[158:161], v[166:169], v[118:121]
	v_mfma_f32_16x16x32_bf16 v[102:105], v[150:153], v[174:177], v[102:105]
	v_mfma_f32_16x16x32_bf16 v[98:101], v[158:161], v[174:177], v[98:101]
	v_mfma_f32_16x16x32_bf16 v[86:89], v[150:153], v[182:185], v[86:89]
	v_mfma_f32_16x16x32_bf16 v[82:85], v[158:161], v[182:185], v[82:85]
	v_mfma_f32_16x16x32_bf16 v[70:73], v[150:153], v[208:211], v[70:73]
	v_mfma_f32_16x16x32_bf16 v[66:69], v[158:161], v[208:211], v[66:69]
	s_barrier
	s_add_i32 s30, s70, s47
	v_lshl_add_u64 v[190:191], s[68:69], 0, v[0:1]
	s_mov_b32 m0, s30
	ds_read_b128 v[162:165], v235 offset:16384
	ds_read_b128 v[166:169], v235 offset:17408
	ds_read_b128 v[170:173], v235 offset:18432
	ds_read_b128 v[174:177], v235 offset:19456
	ds_read_b128 v[178:181], v235 offset:20480
	ds_read_b128 v[182:185], v235 offset:21504
	ds_read_b128 v[204:207], v235 offset:22528
	ds_read_b128 v[208:211], v235 offset:23552
	global_load_lds_dwordx4 v[190:191], off
	s_add_i32 m0, s30, 0x2000
	s_add_u32 s30, s68, s2
	v_lshl_add_u64 v[192:193], s[68:69], 0, v[198:199]
	s_addc_u32 s31, s69, s3
	s_add_i32 s68, s71, s47
	global_load_lds_dwordx4 v[192:193], off
	v_lshl_add_u64 v[212:213], s[30:31], 0, v[0:1]
	s_mov_b32 m0, s68
	v_lshl_add_u64 v[214:215], s[30:31], 0, v[198:199]
	global_load_lds_dwordx4 v[212:213], off
	s_add_i32 m0, s68, 0x2000
	global_load_lds_dwordx4 v[214:215], off
	s_mov_b32 m0, s52
	global_load_lds_dwordx4 v194, s[44:45]
	s_mov_b32 m0, s53
	s_nop 0
	global_load_lds_dwordx4 v196, s[44:45]
	s_waitcnt vmcnt(8)
	s_waitcnt lgkmcnt(0)
	s_barrier
; #define PG8_STAGE(bufoff, gbase, voff) do { _Pragma("unroll") for (int _i = 0; _i < 2; ++_i) \
;         __builtin_amdgcn_global_load_lds((const unsigned*)((const char*)(gbase) + (voff)[_i]), (PG8_LAS unsigned*)(lds + (bufoff) + ldsw + _i * 8192), 16, 0, 0); } while (0)
; #define PG8_LDA(dst, b, h) do { _Pragma("unroll") for (int m = 0; m < 4; ++m) _Pragma("unroll") for (int k = 0; k < 2; ++k) dst[m][k] = *(const PG8_LAS bf16x8*)(lds + PG8_SA(b, h) + aoff + m * 2048 + k * 1024); } while (0)
; #define PG8_LDB(dst, b, h) do { _Pragma("unroll") for (int n = 0; n < 2; ++n) _Pragma("unroll") for (int k = 0; k < 2; ++k) dst[n][k] = *(const PG8_LAS bf16x8*)(lds + PG8_SB(b, h) + boff + n * 2048 + k * 1024); } while (0)
; #define PG8_MMA(ai, bj, At, Bt) do { __builtin_amdgcn_s_setprio(1); _Pragma("unroll") for (int m = 0; m < 4; ++m) _Pragma("unroll") for (int n = 0; n < 2; ++n) _Pragma("unroll") for (int k = 0; k < 2; ++k) \
;         acc[ai][bj][m][n] = __builtin_amdgcn_mfma_f32_16x16x32_bf16(Bt[n][k], At[m][k], acc[ai][bj][m][n], 0, 0, 0); __builtin_amdgcn_s_setprio(0); } while (0)
; #define PG8_WAIT_V(n) asm volatile("s_waitcnt vmcnt(" #n ")" ::: "memory")
; #define PG8_WAIT_L(n) asm volatile("s_waitcnt lgkmcnt(" #n ")" ::: "memory")
; #define PG8_BAR __builtin_amdgcn_s_barrier()
; #define PG8_SCHED __builtin_amdgcn_sched_barrier(0)
; template <class Epi, class Sched, bool ALIGN_EPI = false, bool SP2 = false>
; __device__ __forceinline__ void gemm_phase(PG8_LAS unsigned char* lds, const Gemm g, const Sched& S, const Epi& E, const int wv) {
;     ...
;             PG8_WAIT_V(8); PG8_WAIT_L(0); PG8_BAR; PG8_MMA(1, 0, At, B0); PG8_MMA(1, 1, At, B1); PG8_BAR; PG8_SCHED;
;             PG8_LDB(B0, 1, 0); PG8_LDB(B1, 1, 1); PG8_SCHED; PG8_LDA(At, 1, 0); PG8_STAGE(PG8_SA(0, 1), a2 + hstepA, voffA);
;             PG8_WAIT_V(8); PG8_WAIT_L(0); PG8_BAR; PG8_MMA(0, 0, At, B0); PG8_MMA(0, 1, At, B1); PG8_BAR; PG8_SCHED;
	v_mfma_f32_16x16x32_bf16 v[62:65], v[114:117], v[162:165], v[62:65]
	v_mfma_f32_16x16x32_bf16 v[58:61], v[138:141], v[162:165], v[58:61]
	v_mfma_f32_16x16x32_bf16 v[46:49], v[114:117], v[170:173], v[46:49]
	v_mfma_f32_16x16x32_bf16 v[42:45], v[138:141], v[170:173], v[42:45]
	v_mfma_f32_16x16x32_bf16 v[30:33], v[114:117], v[178:181], v[30:33]
	v_mfma_f32_16x16x32_bf16 v[26:29], v[138:141], v[178:181], v[26:29]
	v_mfma_f32_16x16x32_bf16 v[14:17], v[114:117], v[204:207], v[14:17]
	v_mfma_f32_16x16x32_bf16 v[10:13], v[138:141], v[204:207], v[10:13]
	v_mfma_f32_16x16x32_bf16 v[62:65], v[126:129], v[166:169], v[62:65]
	v_mfma_f32_16x16x32_bf16 v[58:61], v[142:145], v[166:169], v[58:61]
	v_mfma_f32_16x16x32_bf16 v[46:49], v[126:129], v[174:177], v[46:49]
	v_mfma_f32_16x16x32_bf16 v[42:45], v[142:145], v[174:177], v[42:45]
	v_mfma_f32_16x16x32_bf16 v[30:33], v[126:129], v[182:185], v[30:33]
	v_mfma_f32_16x16x32_bf16 v[26:29], v[142:145], v[182:185], v[26:29]
	v_mfma_f32_16x16x32_bf16 v[14:17], v[126:129], v[208:211], v[14:17]
	v_mfma_f32_16x16x32_bf16 v[10:13], v[142:145], v[208:211], v[10:13]
	v_mfma_f32_16x16x32_bf16 v[54:57], v[146:149], v[162:165], v[54:57]
	v_mfma_f32_16x16x32_bf16 v[50:53], v[154:157], v[162:165], v[50:53]
	v_mfma_f32_16x16x32_bf16 v[38:41], v[146:149], v[170:173], v[38:41]
	v_mfma_f32_16x16x32_bf16 v[34:37], v[154:157], v[170:173], v[34:37]
	v_mfma_f32_16x16x32_bf16 v[22:25], v[146:149], v[178:181], v[22:25]
	v_mfma_f32_16x16x32_bf16 v[18:21], v[154:157], v[178:181], v[18:21]
	v_mfma_f32_16x16x32_bf16 v[6:9], v[146:149], v[204:207], v[6:9]
	v_mfma_f32_16x16x32_bf16 v[2:5], v[154:157], v[204:207], v[2:5]
	v_mfma_f32_16x16x32_bf16 v[54:57], v[150:153], v[166:169], v[54:57]
	v_mfma_f32_16x16x32_bf16 v[50:53], v[158:161], v[166:169], v[50:53]
	v_mfma_f32_16x16x32_bf16 v[38:41], v[150:153], v[174:177], v[38:41]
	v_mfma_f32_16x16x32_bf16 v[34:37], v[158:161], v[174:177], v[34:37]
	v_mfma_f32_16x16x32_bf16 v[22:25], v[150:153], v[182:185], v[22:25]
	v_mfma_f32_16x16x32_bf16 v[18:21], v[158:161], v[182:185], v[18:21]
	v_mfma_f32_16x16x32_bf16 v[6:9], v[150:153], v[208:211], v[6:9]
	v_mfma_f32_16x16x32_bf16 v[2:5], v[158:161], v[208:211], v[2:5]
	s_barrier
	s_add_i32 s68, 0, 0x18000
	s_add_i32 s69, 0, 0x1c000
	v_add_u32_e32 v142, s68, v230
	v_add_u32_e32 v158, s69, v230
	ds_read_b128 v[114:117], v142
	ds_read_b128 v[126:129], v142 offset:1024
	ds_read_b128 v[138:141], v142 offset:2048
	ds_read_b128 v[142:145], v142 offset:3072
	ds_read_b128 v[146:149], v158
	ds_read_b128 v[150:153], v158 offset:1024
	ds_read_b128 v[154:157], v158 offset:2048
	ds_read_b128 v[158:161], v158 offset:3072
	s_add_u32 s30, s44, 0x180000
	s_addc_u32 s31, s45, 0
	s_mov_b32 m0, s54
	ds_read_b128 v[162:165], v235 offset:32768
	ds_read_b128 v[166:169], v235 offset:33792
	ds_read_b128 v[170:173], v235 offset:34816
	ds_read_b128 v[174:177], v235 offset:35840
	ds_read_b128 v[178:181], v235 offset:36864
	ds_read_b128 v[182:185], v235 offset:37888
	ds_read_b128 v[204:207], v235 offset:38912
	ds_read_b128 v[208:211], v235 offset:39936
	global_load_lds_dwordx4 v194, s[30:31]
	s_mov_b32 m0, s55
	s_nop 0
	global_load_lds_dwordx4 v196, s[30:31]
	s_waitcnt vmcnt(8)
	s_waitcnt lgkmcnt(0)
	s_barrier
	v_mfma_f32_16x16x32_bf16 v[134:137], v[114:117], v[162:165], v[134:137]
	v_mfma_f32_16x16x32_bf16 v[130:133], v[138:141], v[162:165], v[130:133]
	v_mfma_f32_16x16x32_bf16 v[110:113], v[114:117], v[170:173], v[110:113]
	v_mfma_f32_16x16x32_bf16 v[106:109], v[138:141], v[170:173], v[106:109]
	v_mfma_f32_16x16x32_bf16 v[94:97], v[114:117], v[178:181], v[94:97]
	v_mfma_f32_16x16x32_bf16 v[90:93], v[138:141], v[178:181], v[90:93]
	v_mfma_f32_16x16x32_bf16 v[78:81], v[114:117], v[204:207], v[78:81]
	v_mfma_f32_16x16x32_bf16 v[74:77], v[138:141], v[204:207], v[74:77]
	v_mfma_f32_16x16x32_bf16 v[134:137], v[126:129], v[166:169], v[134:137]
	v_mfma_f32_16x16x32_bf16 v[130:133], v[142:145], v[166:169], v[130:133]
	v_mfma_f32_16x16x32_bf16 v[110:113], v[126:129], v[174:177], v[110:113]
	v_mfma_f32_16x16x32_bf16 v[106:109], v[142:145], v[174:177], v[106:109]
	v_mfma_f32_16x16x32_bf16 v[94:97], v[126:129], v[182:185], v[94:97]
	v_mfma_f32_16x16x32_bf16 v[90:93], v[142:145], v[182:185], v[90:93]
	v_mfma_f32_16x16x32_bf16 v[78:81], v[126:129], v[208:211], v[78:81]
	v_mfma_f32_16x16x32_bf16 v[74:77], v[142:145], v[208:211], v[74:77]
	v_mfma_f32_16x16x32_bf16 v[122:125], v[146:149], v[162:165], v[122:125]
	v_mfma_f32_16x16x32_bf16 v[118:121], v[154:157], v[162:165], v[118:121]
	v_mfma_f32_16x16x32_bf16 v[102:105], v[146:149], v[170:173], v[102:105]
	v_mfma_f32_16x16x32_bf16 v[98:101], v[154:157], v[170:173], v[98:101]
	v_mfma_f32_16x16x32_bf16 v[86:89], v[146:149], v[178:181], v[86:89]
	v_mfma_f32_16x16x32_bf16 v[82:85], v[154:157], v[178:181], v[82:85]
	v_mfma_f32_16x16x32_bf16 v[70:73], v[146:149], v[204:207], v[70:73]
	v_mfma_f32_16x16x32_bf16 v[66:69], v[154:157], v[204:207], v[66:69]
	v_mfma_f32_16x16x32_bf16 v[122:125], v[150:153], v[166:169], v[122:125]
	v_mfma_f32_16x16x32_bf16 v[118:121], v[158:161], v[166:169], v[118:121]
	v_mfma_f32_16x16x32_bf16 v[102:105], v[150:153], v[174:177], v[102:105]
	v_mfma_f32_16x16x32_bf16 v[98:101], v[158:161], v[174:177], v[98:101]
	v_mfma_f32_16x16x32_bf16 v[86:89], v[150:153], v[182:185], v[86:89]
	v_mfma_f32_16x16x32_bf16 v[82:85], v[158:161], v[182:185], v[82:85]
	v_mfma_f32_16x16x32_bf16 v[70:73], v[150:153], v[208:211], v[70:73]
	v_mfma_f32_16x16x32_bf16 v[66:69], v[158:161], v[208:211], v[66:69]
	s_barrier
; #define PG8_STAGE(bufoff, gbase, voff) do { _Pragma("unroll") for (int _i = 0; _i < 2; ++_i) \
;         __builtin_amdgcn_global_load_lds((const unsigned*)((const char*)(gbase) + (voff)[_i]), (PG8_LAS unsigned*)(lds + (bufoff) + ldsw + _i * 8192), 16, 0, 0); } while (0)
; #define PG8_LDA(dst, b, h) do { _Pragma("unroll") for (int m = 0; m < 4; ++m) _Pragma("unroll") for (int k = 0; k < 2; ++k) dst[m][k] = *(const PG8_LAS bf16x8*)(lds + PG8_SA(b, h) + aoff + m * 2048 + k * 1024); } while (0)
; #define PG8_MMA(ai, bj, At, Bt) do { __builtin_amdgcn_s_setprio(1); _Pragma("unroll") for (int m = 0; m < 4; ++m) _Pragma("unroll") for (int n = 0; n < 2; ++n) _Pragma("unroll") for (int k = 0; k < 2; ++k) \
;         acc[ai][bj][m][n] = __builtin_amdgcn_mfma_f32_16x16x32_bf16(Bt[n][k], At[m][k], acc[ai][bj][m][n], 0, 0, 0); __builtin_amdgcn_s_setprio(0); } while (0)
; #define PG8_WAIT_V(n) asm volatile("s_waitcnt vmcnt(" #n ")" ::: "memory")
; #define PG8_WAIT_L(n) asm volatile("s_waitcnt lgkmcnt(" #n ")" ::: "memory")
; #define PG8_BAR __builtin_amdgcn_s_barrier()
; #define PG8_SCHED __builtin_amdgcn_sched_barrier(0)
; template <class Epi, class Sched, bool ALIGN_EPI = false, bool SP2 = false>
; __device__ __forceinline__ void gemm_phase(PG8_LAS unsigned char* lds, const Gemm g, const Sched& S, const Epi& E, const int wv) {
;     ...
;             PG8_LDA(At, 1, 1); PG8_STAGE(PG8_SB(1, 0), b3, voffB); PG8_STAGE(PG8_SB(1, 1), b3 + hstepB, voffB); PG8_STAGE(PG8_SA(1, 0), a3, voffA);
;             PG8_WAIT_V(8); PG8_WAIT_L(0); PG8_BAR; PG8_MMA(1, 0, At, B0); PG8_MMA(1, 1, At, B1); PG8_BAR; PG8_SCHED;
	s_add_i32 s30, s68, s47
	s_add_i32 m0, s30, 0xffffff80
	ds_read_b128 v[162:165], v235 offset:49152
	ds_read_b128 v[166:169], v235 offset:50176
	ds_read_b128 v[170:173], v235 offset:51200
	ds_read_b128 v[174:177], v235 offset:52224
	ds_read_b128 v[178:181], v235 offset:53248
	ds_read_b128 v[182:185], v235 offset:54272
	ds_read_b128 v[204:207], v235 offset:55296
	ds_read_b128 v[208:211], v235 offset:56320
	global_load_lds_dwordx4 v[190:191], off offset:128
	s_add_i32 m0, s30, 0x1f80
	s_add_i32 s30, s69, s47
	global_load_lds_dwordx4 v[192:193], off offset:128
	s_add_i32 m0, s30, 0xffffff80
	s_nop 0
	global_load_lds_dwordx4 v[212:213], off offset:128
	s_add_i32 m0, s30, 0x1f80
	s_nop 0
	global_load_lds_dwordx4 v[214:215], off offset:128
	s_add_i32 m0, s57, 0xffffff80
	s_nop 0
	global_load_lds_dwordx4 v194, s[44:45] offset:128
	s_add_i32 m0, s58, 0xffffff80
	s_nop 0
	global_load_lds_dwordx4 v196, s[44:45] offset:128
	s_waitcnt vmcnt(8)
	s_waitcnt lgkmcnt(0)
	s_barrier
	v_mfma_f32_16x16x32_bf16 v[62:65], v[114:117], v[162:165], v[62:65]
	v_mfma_f32_16x16x32_bf16 v[58:61], v[138:141], v[162:165], v[58:61]
	v_mfma_f32_16x16x32_bf16 v[46:49], v[114:117], v[170:173], v[46:49]
	v_mfma_f32_16x16x32_bf16 v[42:45], v[138:141], v[170:173], v[42:45]
	v_mfma_f32_16x16x32_bf16 v[30:33], v[114:117], v[178:181], v[30:33]
	v_mfma_f32_16x16x32_bf16 v[26:29], v[138:141], v[178:181], v[26:29]
	v_mfma_f32_16x16x32_bf16 v[14:17], v[114:117], v[204:207], v[14:17]
	v_mfma_f32_16x16x32_bf16 v[10:13], v[138:141], v[204:207], v[10:13]
	v_mfma_f32_16x16x32_bf16 v[62:65], v[126:129], v[166:169], v[62:65]
	v_mfma_f32_16x16x32_bf16 v[58:61], v[142:145], v[166:169], v[58:61]
	v_mfma_f32_16x16x32_bf16 v[46:49], v[126:129], v[174:177], v[46:49]
	v_mfma_f32_16x16x32_bf16 v[42:45], v[142:145], v[174:177], v[42:45]
	v_mfma_f32_16x16x32_bf16 v[30:33], v[126:129], v[182:185], v[30:33]
	v_mfma_f32_16x16x32_bf16 v[26:29], v[142:145], v[182:185], v[26:29]
	v_mfma_f32_16x16x32_bf16 v[14:17], v[126:129], v[208:211], v[14:17]
	v_mfma_f32_16x16x32_bf16 v[10:13], v[142:145], v[208:211], v[10:13]
	v_mfma_f32_16x16x32_bf16 v[54:57], v[146:149], v[162:165], v[54:57]
	v_mfma_f32_16x16x32_bf16 v[50:53], v[154:157], v[162:165], v[50:53]
	v_mfma_f32_16x16x32_bf16 v[38:41], v[146:149], v[170:173], v[38:41]
	v_mfma_f32_16x16x32_bf16 v[34:37], v[154:157], v[170:173], v[34:37]
	v_mfma_f32_16x16x32_bf16 v[22:25], v[146:149], v[178:181], v[22:25]
	v_mfma_f32_16x16x32_bf16 v[18:21], v[154:157], v[178:181], v[18:21]
	v_mfma_f32_16x16x32_bf16 v[6:9], v[146:149], v[204:207], v[6:9]
	v_mfma_f32_16x16x32_bf16 v[2:5], v[154:157], v[204:207], v[2:5]
	v_mfma_f32_16x16x32_bf16 v[54:57], v[150:153], v[166:169], v[54:57]
	v_mfma_f32_16x16x32_bf16 v[50:53], v[158:161], v[166:169], v[50:53]
	v_mfma_f32_16x16x32_bf16 v[38:41], v[150:153], v[174:177], v[38:41]
	v_mfma_f32_16x16x32_bf16 v[34:37], v[158:161], v[174:177], v[34:37]
	v_mfma_f32_16x16x32_bf16 v[22:25], v[150:153], v[182:185], v[22:25]
	v_mfma_f32_16x16x32_bf16 v[18:21], v[158:161], v[182:185], v[18:21]
	v_mfma_f32_16x16x32_bf16 v[6:9], v[150:153], v[208:211], v[6:9]
	v_mfma_f32_16x16x32_bf16 v[2:5], v[158:161], v[208:211], v[2:5]
	s_barrier
	s_add_u32 s65, s65, 0x100
	s_addc_u32 s66, s66, 0
	s_cmp_ge_i32 s67, s56
	s_mov_b64 s[30:31], s[34:35]
	s_mov_b32 s44, s67
	s_cbranch_scc0 .LBB0_990
	s_movk_i32 s68, 0x4000
	s_movk_i32 s69, 0x6000
	s_mov_b32 s70, 0x18000
	s_mov_b32 s71, 0x3f317217
	v_readlane_b32 s67, v255, 30
	s_and_b64 vcc, exec, s[28:29]
	s_cbranch_vccz .LBB0_966

; #define PG8_STAGE(bufoff, gbase, voff) do { _Pragma("unroll") for (int _i = 0; _i < 2; ++_i) \
;         __builtin_amdgcn_global_load_lds((const unsigned*)((const char*)(gbase) + (voff)[_i]), (PG8_LAS unsigned*)(lds + (bufoff) + ldsw + _i * 8192), 16, 0, 0); } while (0)
; #define PG8_LDA(dst, b, h) do { _Pragma("unroll") for (int m = 0; m < 4; ++m) _Pragma("unroll") for (int k = 0; k < 2; ++k) dst[m][k] = *(const PG8_LAS bf16x8*)(lds + PG8_SA(b, h) + aoff + m * 2048 + k * 1024); } while (0)
; #define PG8_LDB(dst, b, h) do { _Pragma("unroll") for (int n = 0; n < 2; ++n) _Pragma("unroll") for (int k = 0; k < 2; ++k) dst[n][k] = *(const PG8_LAS bf16x8*)(lds + PG8_SB(b, h) + boff + n * 2048 + k * 1024); } while (0)
; #define PG8_MMA(ai, bj, At, Bt) do { __builtin_amdgcn_s_setprio(1); _Pragma("unroll") for (int m = 0; m < 4; ++m) _Pragma("unroll") for (int n = 0; n < 2; ++n) _Pragma("unroll") for (int k = 0; k < 2; ++k) \
;         acc[ai][bj][m][n] = __builtin_amdgcn_mfma_f32_16x16x32_bf16(Bt[n][k], At[m][k], acc[ai][bj][m][n], 0, 0, 0); __builtin_amdgcn_s_setprio(0); } while (0)
; #define PG8_WAIT_V(n) asm volatile("s_waitcnt vmcnt(" #n ")" ::: "memory")
; #define PG8_WAIT_L(n) asm volatile("s_waitcnt lgkmcnt(" #n ")" ::: "memory")
; template <class Epi, class Sched, bool ALIGN_EPI = false, bool SP2 = false>
; __device__ __forceinline__ void gemm_phase(PG8_LAS unsigned char* lds, const Gemm g, const Sched& S, const Epi& E, const int wv) {
;     ...
;             const bool last = (t == nt - 2);
;             const char* a1 = cA + (size_t)(t + 1) * kstep;
;             const char* a2 = last ? nA : cA + (size_t)(t + 2) * kstep; const char* b2 = last ? nB : cB + (size_t)(t + 2) * kstep;
;             const char* a3 = a2 + kstep; const char* b3 = b2 + kstep;
;             if (last && has_next) S.a_ready(nxt);
;             if constexpr (SP2) {
;             PG8_LDB(B0, 0, 0); PG8_LDB(B1, 0, 1); PG8_SCHED; PG8_LDA(At, 0, 0); PG8_STAGE(PG8_SA(1, 1), a1 + hstepA, voffA);
;             PG8_WAIT_V(8); PG8_WAIT_L(0); PG8_BAR; PG8_MMA(0, 0, At, B0); PG8_MMA(0, 1, At, B1); PG8_BAR; PG8_SCHED;
;             PG8_LDA(At, 0, 1); PG8_STAGE(PG8_SB(0, 0), b2, voffB); PG8_STAGE(PG8_SB(0, 1), b2 + hstepB, voffB); PG8_STAGE(PG8_SA(0, 0), a2, voffA);
;             PG8_WAIT_V(8); PG8_WAIT_L(0); PG8_BAR; PG8_MMA(1, 0, At, B0); PG8_MMA(1, 1, At, B1); PG8_BAR; PG8_SCHED;
.LBB0_1495:
	s_add_i32 s52, s46, 2
	s_add_u32 s14, s48, 0x100
	s_addc_u32 s15, s49, 0
	s_add_i32 s53, 0, 0x10000
	s_cmp_eq_u32 s72, s46
	s_cselect_b32 s47, s11, s15
	s_cselect_b32 s46, s13, s14
	s_cselect_b32 s77, s87, s51
	s_cselect_b32 s76, s86, s35
	s_add_i32 s78, 0, 0x14000
	v_add_u32_e32 v150, s53, v208
	v_add_u32_e32 v166, s78, v208
	ds_read_b128 v[138:141], v150
	ds_read_b128 v[142:145], v150 offset:1024
	ds_read_b128 v[146:149], v150 offset:2048
	ds_read_b128 v[150:153], v150 offset:3072
	ds_read_b128 v[154:157], v166
	ds_read_b128 v[158:161], v166 offset:1024
	ds_read_b128 v[162:165], v166 offset:2048
	ds_read_b128 v[166:169], v166 offset:3072
	s_add_i32 m0, s64, 0xc000
	ds_read_b128 v[194:197], v211
	ds_read_b128 v[198:201], v211 offset:1024
	ds_read_b128 v[202:205], v211 offset:2048
	ds_read_b128 v[214:217], v211 offset:3072
	ds_read_b128 v[228:231], v211 offset:4096
	ds_read_b128 v[232:235], v211 offset:5120
	ds_read_b128 v[236:239], v211 offset:6144
	ds_read_b128 v[240:243], v211 offset:7168
	global_load_lds_dwordx4 v182, s[48:49]
	v_lshl_add_u64 v[190:191], s[48:49], 0, v[184:185]
	s_add_i32 m0, s64, 0xe000
	s_nop 0
	global_load_lds_dwordx4 v[190:191], off
	s_waitcnt vmcnt(8)
	s_waitcnt lgkmcnt(0)
	s_barrier
	v_mfma_f32_16x16x32_bf16 v[118:121], v[138:141], v[194:197], v[118:121]
	v_mfma_f32_16x16x32_bf16 v[46:49], v[146:149], v[194:197], v[46:49]
	v_mfma_f32_16x16x32_bf16 v[110:113], v[138:141], v[202:205], v[110:113]
	v_mfma_f32_16x16x32_bf16 v[38:41], v[146:149], v[202:205], v[38:41]
	v_mfma_f32_16x16x32_bf16 v[134:137], v[138:141], v[228:231], v[134:137]
	v_mfma_f32_16x16x32_bf16 v[62:65], v[146:149], v[228:231], v[62:65]
	v_mfma_f32_16x16x32_bf16 v[130:133], v[138:141], v[236:239], v[130:133]
	v_mfma_f32_16x16x32_bf16 v[58:61], v[146:149], v[236:239], v[58:61]
	v_mfma_f32_16x16x32_bf16 v[118:121], v[142:145], v[198:201], v[118:121]
	v_mfma_f32_16x16x32_bf16 v[46:49], v[150:153], v[198:201], v[46:49]
	v_mfma_f32_16x16x32_bf16 v[110:113], v[142:145], v[214:217], v[110:113]
	v_mfma_f32_16x16x32_bf16 v[38:41], v[150:153], v[214:217], v[38:41]
	v_mfma_f32_16x16x32_bf16 v[134:137], v[142:145], v[232:235], v[134:137]
	v_mfma_f32_16x16x32_bf16 v[62:65], v[150:153], v[232:235], v[62:65]
	v_mfma_f32_16x16x32_bf16 v[130:133], v[142:145], v[240:243], v[130:133]
	v_mfma_f32_16x16x32_bf16 v[58:61], v[150:153], v[240:243], v[58:61]
	v_mfma_f32_16x16x32_bf16 v[114:117], v[154:157], v[194:197], v[114:117]
	v_mfma_f32_16x16x32_bf16 v[42:45], v[162:165], v[194:197], v[42:45]
	v_mfma_f32_16x16x32_bf16 v[106:109], v[154:157], v[202:205], v[106:109]
	v_mfma_f32_16x16x32_bf16 v[34:37], v[162:165], v[202:205], v[34:37]
	v_mfma_f32_16x16x32_bf16 v[126:129], v[154:157], v[228:231], v[126:129]
	v_mfma_f32_16x16x32_bf16 v[54:57], v[162:165], v[228:231], v[54:57]
	v_mfma_f32_16x16x32_bf16 v[122:125], v[154:157], v[236:239], v[122:125]
	v_mfma_f32_16x16x32_bf16 v[50:53], v[162:165], v[236:239], v[50:53]
	v_mfma_f32_16x16x32_bf16 v[114:117], v[158:161], v[198:201], v[114:117]
	v_mfma_f32_16x16x32_bf16 v[42:45], v[166:169], v[198:201], v[42:45]
	v_mfma_f32_16x16x32_bf16 v[106:109], v[158:161], v[214:217], v[106:109]
	v_mfma_f32_16x16x32_bf16 v[34:37], v[166:169], v[214:217], v[34:37]
	v_mfma_f32_16x16x32_bf16 v[126:129], v[158:161], v[232:235], v[126:129]
	v_mfma_f32_16x16x32_bf16 v[54:57], v[166:169], v[232:235], v[54:57]
	v_mfma_f32_16x16x32_bf16 v[122:125], v[158:161], v[240:243], v[122:125]
	v_mfma_f32_16x16x32_bf16 v[50:53], v[166:169], v[240:243], v[50:53]
	s_barrier
	s_add_i32 s48, s53, s63
	s_mov_b32 m0, s48
	ds_read_b128 v[194:197], v211 offset:16384
	ds_read_b128 v[198:201], v211 offset:17408
	ds_read_b128 v[202:205], v211 offset:18432
	ds_read_b128 v[214:217], v211 offset:19456
	ds_read_b128 v[228:231], v211 offset:20480
	ds_read_b128 v[232:235], v211 offset:21504
	ds_read_b128 v[236:239], v211 offset:22528
	ds_read_b128 v[240:243], v211 offset:23552
	global_load_lds_dwordx4 v0, s[76:77]
	s_add_i32 m0, s48, 0x2000
	s_add_u32 s48, s76, s16
	s_addc_u32 s49, s77, s17
	s_add_i32 s53, s78, s63
	global_load_lds_dwordx4 v174, s[76:77]
	v_lshl_add_u64 v[218:219], s[48:49], 0, v[0:1]
	s_mov_b32 m0, s53
	v_lshl_add_u64 v[244:245], s[48:49], 0, v[174:175]
	global_load_lds_dwordx4 v[218:219], off
	s_add_i32 m0, s53, 0x2000
	v_lshl_add_u64 v[246:247], s[46:47], 0, v[170:171]
	global_load_lds_dwordx4 v[244:245], off
	s_mov_b32 m0, s64
	v_lshl_add_u64 v[248:249], s[46:47], 0, v[172:173]
	global_load_lds_dwordx4 v[246:247], off
	s_mov_b32 m0, s65
	s_nop 0
	global_load_lds_dwordx4 v[248:249], off
	s_waitcnt vmcnt(8)
	s_waitcnt lgkmcnt(0)
	s_barrier
; #define PG8_STAGE(bufoff, gbase, voff) do { _Pragma("unroll") for (int _i = 0; _i < 2; ++_i) \
;         __builtin_amdgcn_global_load_lds((const unsigned*)((const char*)(gbase) + (voff)[_i]), (PG8_LAS unsigned*)(lds + (bufoff) + ldsw + _i * 8192), 16, 0, 0); } while (0)
; #define PG8_LDA(dst, b, h) do { _Pragma("unroll") for (int m = 0; m < 4; ++m) _Pragma("unroll") for (int k = 0; k < 2; ++k) dst[m][k] = *(const PG8_LAS bf16x8*)(lds + PG8_SA(b, h) + aoff + m * 2048 + k * 1024); } while (0)
; #define PG8_LDB(dst, b, h) do { _Pragma("unroll") for (int n = 0; n < 2; ++n) _Pragma("unroll") for (int k = 0; k < 2; ++k) dst[n][k] = *(const PG8_LAS bf16x8*)(lds + PG8_SB(b, h) + boff + n * 2048 + k * 1024); } while (0)
; #define PG8_MMA(ai, bj, At, Bt) do { __builtin_amdgcn_s_setprio(1); _Pragma("unroll") for (int m = 0; m < 4; ++m) _Pragma("unroll") for (int n = 0; n < 2; ++n) _Pragma("unroll") for (int k = 0; k < 2; ++k) \
;         acc[ai][bj][m][n] = __builtin_amdgcn_mfma_f32_16x16x32_bf16(Bt[n][k], At[m][k], acc[ai][bj][m][n], 0, 0, 0); __builtin_amdgcn_s_setprio(0); } while (0)
; #define PG8_WAIT_V(n) asm volatile("s_waitcnt vmcnt(" #n ")" ::: "memory")
; #define PG8_WAIT_L(n) asm volatile("s_waitcnt lgkmcnt(" #n ")" ::: "memory")
; #define PG8_BAR __builtin_amdgcn_s_barrier()
; #define PG8_SCHED __builtin_amdgcn_sched_barrier(0)
; template <class Epi, class Sched, bool ALIGN_EPI = false, bool SP2 = false>
; __device__ __forceinline__ void gemm_phase(PG8_LAS unsigned char* lds, const Gemm g, const Sched& S, const Epi& E, const int wv) {
;     ...
;             PG8_WAIT_V(8); PG8_WAIT_L(0); PG8_BAR; PG8_MMA(1, 0, At, B0); PG8_MMA(1, 1, At, B1); PG8_BAR; PG8_SCHED;
;             PG8_LDB(B0, 1, 0); PG8_LDB(B1, 1, 1); PG8_SCHED; PG8_LDA(At, 1, 0); PG8_STAGE(PG8_SA(0, 1), a2 + hstepA, voffA);
;             PG8_WAIT_V(8); PG8_WAIT_L(0); PG8_BAR; PG8_MMA(0, 0, At, B0); PG8_MMA(0, 1, At, B1); PG8_BAR; PG8_SCHED;
	v_mfma_f32_16x16x32_bf16 v[86:89], v[138:141], v[194:197], v[86:89]
	v_mfma_f32_16x16x32_bf16 v[14:17], v[146:149], v[194:197], v[14:17]
	v_mfma_f32_16x16x32_bf16 v[70:73], v[138:141], v[202:205], v[70:73]
	v_mfma_f32_16x16x32_bf16 v[6:9], v[146:149], v[202:205], v[6:9]
	v_mfma_f32_16x16x32_bf16 v[102:105], v[138:141], v[228:231], v[102:105]
	v_mfma_f32_16x16x32_bf16 v[30:33], v[146:149], v[228:231], v[30:33]
	v_mfma_f32_16x16x32_bf16 v[98:101], v[138:141], v[236:239], v[98:101]
	v_mfma_f32_16x16x32_bf16 v[26:29], v[146:149], v[236:239], v[26:29]
	v_mfma_f32_16x16x32_bf16 v[86:89], v[142:145], v[198:201], v[86:89]
	v_mfma_f32_16x16x32_bf16 v[14:17], v[150:153], v[198:201], v[14:17]
	v_mfma_f32_16x16x32_bf16 v[70:73], v[142:145], v[214:217], v[70:73]
	v_mfma_f32_16x16x32_bf16 v[6:9], v[150:153], v[214:217], v[6:9]
	v_mfma_f32_16x16x32_bf16 v[102:105], v[142:145], v[232:235], v[102:105]
	v_mfma_f32_16x16x32_bf16 v[30:33], v[150:153], v[232:235], v[30:33]
	v_mfma_f32_16x16x32_bf16 v[98:101], v[142:145], v[240:243], v[98:101]
	v_mfma_f32_16x16x32_bf16 v[26:29], v[150:153], v[240:243], v[26:29]
	v_mfma_f32_16x16x32_bf16 v[82:85], v[154:157], v[194:197], v[82:85]
	v_mfma_f32_16x16x32_bf16 v[10:13], v[162:165], v[194:197], v[10:13]
	v_mfma_f32_16x16x32_bf16 v[66:69], v[154:157], v[202:205], v[66:69]
	v_mfma_f32_16x16x32_bf16 v[2:5], v[162:165], v[202:205], v[2:5]
	v_mfma_f32_16x16x32_bf16 v[94:97], v[154:157], v[228:231], v[94:97]
	v_mfma_f32_16x16x32_bf16 v[22:25], v[162:165], v[228:231], v[22:25]
	v_mfma_f32_16x16x32_bf16 v[90:93], v[154:157], v[236:239], v[90:93]
	v_mfma_f32_16x16x32_bf16 v[18:21], v[162:165], v[236:239], v[18:21]
	v_mfma_f32_16x16x32_bf16 v[82:85], v[158:161], v[198:201], v[82:85]
	v_mfma_f32_16x16x32_bf16 v[10:13], v[166:169], v[198:201], v[10:13]
	v_mfma_f32_16x16x32_bf16 v[66:69], v[158:161], v[214:217], v[66:69]
	v_mfma_f32_16x16x32_bf16 v[2:5], v[166:169], v[214:217], v[2:5]
	v_mfma_f32_16x16x32_bf16 v[94:97], v[158:161], v[232:235], v[94:97]
	v_mfma_f32_16x16x32_bf16 v[22:25], v[166:169], v[232:235], v[22:25]
	v_mfma_f32_16x16x32_bf16 v[90:93], v[158:161], v[240:243], v[90:93]
	v_mfma_f32_16x16x32_bf16 v[18:21], v[166:169], v[240:243], v[18:21]
	s_barrier
	s_add_i32 s48, 0, 0x18000
	s_add_i32 s49, 0, 0x1c000
	v_add_u32_e32 v150, s48, v208
	v_add_u32_e32 v166, s49, v208
	ds_read_b128 v[138:141], v150
	ds_read_b128 v[142:145], v150 offset:1024
	ds_read_b128 v[146:149], v150 offset:2048
	ds_read_b128 v[150:153], v150 offset:3072
	ds_read_b128 v[154:157], v166
	ds_read_b128 v[158:161], v166 offset:1024
	ds_read_b128 v[162:165], v166 offset:2048
	ds_read_b128 v[166:169], v166 offset:3072
	s_add_u32 s46, s46, 0x80000
	s_addc_u32 s47, s47, 0
	s_mov_b32 m0, s66
	ds_read_b128 v[194:197], v211 offset:32768
	ds_read_b128 v[198:201], v211 offset:33792
	ds_read_b128 v[202:205], v211 offset:34816
	ds_read_b128 v[214:217], v211 offset:35840
	ds_read_b128 v[228:231], v211 offset:36864
	ds_read_b128 v[232:235], v211 offset:37888
	ds_read_b128 v[236:239], v211 offset:38912
	ds_read_b128 v[240:243], v211 offset:39936
	global_load_lds_dwordx4 v170, s[46:47]
	s_mov_b32 m0, s67
	s_nop 0
	global_load_lds_dwordx4 v172, s[46:47]
	s_waitcnt vmcnt(8)
	s_waitcnt lgkmcnt(0)
	s_barrier
	v_mfma_f32_16x16x32_bf16 v[118:121], v[138:141], v[194:197], v[118:121]
	v_mfma_f32_16x16x32_bf16 v[46:49], v[146:149], v[194:197], v[46:49]
	v_mfma_f32_16x16x32_bf16 v[110:113], v[138:141], v[202:205], v[110:113]
	v_mfma_f32_16x16x32_bf16 v[38:41], v[146:149], v[202:205], v[38:41]
	v_mfma_f32_16x16x32_bf16 v[134:137], v[138:141], v[228:231], v[134:137]
	v_mfma_f32_16x16x32_bf16 v[62:65], v[146:149], v[228:231], v[62:65]
	v_mfma_f32_16x16x32_bf16 v[130:133], v[138:141], v[236:239], v[130:133]
	v_mfma_f32_16x16x32_bf16 v[58:61], v[146:149], v[236:239], v[58:61]
	v_mfma_f32_16x16x32_bf16 v[118:121], v[142:145], v[198:201], v[118:121]
	v_mfma_f32_16x16x32_bf16 v[46:49], v[150:153], v[198:201], v[46:49]
	v_mfma_f32_16x16x32_bf16 v[110:113], v[142:145], v[214:217], v[110:113]
	v_mfma_f32_16x16x32_bf16 v[38:41], v[150:153], v[214:217], v[38:41]
	v_mfma_f32_16x16x32_bf16 v[134:137], v[142:145], v[232:235], v[134:137]
	v_mfma_f32_16x16x32_bf16 v[62:65], v[150:153], v[232:235], v[62:65]
	v_mfma_f32_16x16x32_bf16 v[130:133], v[142:145], v[240:243], v[130:133]
	v_mfma_f32_16x16x32_bf16 v[58:61], v[150:153], v[240:243], v[58:61]
	v_mfma_f32_16x16x32_bf16 v[114:117], v[154:157], v[194:197], v[114:117]
	v_mfma_f32_16x16x32_bf16 v[42:45], v[162:165], v[194:197], v[42:45]
	v_mfma_f32_16x16x32_bf16 v[106:109], v[154:157], v[202:205], v[106:109]
	v_mfma_f32_16x16x32_bf16 v[34:37], v[162:165], v[202:205], v[34:37]
	v_mfma_f32_16x16x32_bf16 v[126:129], v[154:157], v[228:231], v[126:129]
	v_mfma_f32_16x16x32_bf16 v[54:57], v[162:165], v[228:231], v[54:57]
	v_mfma_f32_16x16x32_bf16 v[122:125], v[154:157], v[236:239], v[122:125]
	v_mfma_f32_16x16x32_bf16 v[50:53], v[162:165], v[236:239], v[50:53]
	v_mfma_f32_16x16x32_bf16 v[114:117], v[158:161], v[198:201], v[114:117]
	v_mfma_f32_16x16x32_bf16 v[42:45], v[166:169], v[198:201], v[42:45]
	v_mfma_f32_16x16x32_bf16 v[106:109], v[158:161], v[214:217], v[106:109]
	v_mfma_f32_16x16x32_bf16 v[34:37], v[166:169], v[214:217], v[34:37]
	v_mfma_f32_16x16x32_bf16 v[126:129], v[158:161], v[232:235], v[126:129]
	v_mfma_f32_16x16x32_bf16 v[54:57], v[166:169], v[232:235], v[54:57]
	v_mfma_f32_16x16x32_bf16 v[122:125], v[158:161], v[240:243], v[122:125]
	v_mfma_f32_16x16x32_bf16 v[50:53], v[166:169], v[240:243], v[50:53]
	s_barrier
; #define PG8_STAGE(bufoff, gbase, voff) do { _Pragma("unroll") for (int _i = 0; _i < 2; ++_i) \
;         __builtin_amdgcn_global_load_lds((const unsigned*)((const char*)(gbase) + (voff)[_i]), (PG8_LAS unsigned*)(lds + (bufoff) + ldsw + _i * 8192), 16, 0, 0); } while (0)
; #define PG8_LDA(dst, b, h) do { _Pragma("unroll") for (int m = 0; m < 4; ++m) _Pragma("unroll") for (int k = 0; k < 2; ++k) dst[m][k] = *(const PG8_LAS bf16x8*)(lds + PG8_SA(b, h) + aoff + m * 2048 + k * 1024); } while (0)
; #define PG8_MMA(ai, bj, At, Bt) do { __builtin_amdgcn_s_setprio(1); _Pragma("unroll") for (int m = 0; m < 4; ++m) _Pragma("unroll") for (int n = 0; n < 2; ++n) _Pragma("unroll") for (int k = 0; k < 2; ++k) \
;         acc[ai][bj][m][n] = __builtin_amdgcn_mfma_f32_16x16x32_bf16(Bt[n][k], At[m][k], acc[ai][bj][m][n], 0, 0, 0); __builtin_amdgcn_s_setprio(0); } while (0)
; #define PG8_WAIT_V(n) asm volatile("s_waitcnt vmcnt(" #n ")" ::: "memory")
; #define PG8_WAIT_L(n) asm volatile("s_waitcnt lgkmcnt(" #n ")" ::: "memory")
; #define PG8_BAR __builtin_amdgcn_s_barrier()
; #define PG8_SCHED __builtin_amdgcn_sched_barrier(0)
; template <class Epi, class Sched, bool ALIGN_EPI = false, bool SP2 = false>
; __device__ __forceinline__ void gemm_phase(PG8_LAS unsigned char* lds, const Gemm g, const Sched& S, const Epi& E, const int wv) {
;     ...
;             PG8_LDA(At, 1, 1); PG8_STAGE(PG8_SB(1, 0), b3, voffB); PG8_STAGE(PG8_SB(1, 1), b3 + hstepB, voffB); PG8_STAGE(PG8_SA(1, 0), a3, voffA);
;             PG8_WAIT_V(8); PG8_WAIT_L(0); PG8_BAR; PG8_MMA(1, 0, At, B0); PG8_MMA(1, 1, At, B1); PG8_BAR; PG8_SCHED;
	s_add_i32 s46, s48, s63
	s_add_i32 m0, s46, 0xffffff80
	ds_read_b128 v[194:197], v211 offset:49152
	ds_read_b128 v[198:201], v211 offset:50176
	ds_read_b128 v[202:205], v211 offset:51200
	ds_read_b128 v[214:217], v211 offset:52224
	ds_read_b128 v[228:231], v211 offset:53248
	ds_read_b128 v[232:235], v211 offset:54272
	ds_read_b128 v[236:239], v211 offset:55296
	ds_read_b128 v[240:243], v211 offset:56320
	global_load_lds_dwordx4 v0, s[76:77] offset:128
	s_add_i32 m0, s46, 0x1f80
	s_add_i32 s46, s49, s63
	global_load_lds_dwordx4 v174, s[76:77] offset:128
	s_add_i32 m0, s46, 0xffffff80
	s_nop 0
	global_load_lds_dwordx4 v[218:219], off offset:128
	s_add_i32 m0, s46, 0x1f80
	s_nop 0
	global_load_lds_dwordx4 v[244:245], off offset:128
	s_add_i32 m0, s70, 0xffffff80
	s_nop 0
	global_load_lds_dwordx4 v[246:247], off offset:128
	s_add_i32 m0, s71, 0xffffff80
	s_nop 0
	global_load_lds_dwordx4 v[248:249], off offset:128
	s_waitcnt vmcnt(8)
	s_waitcnt lgkmcnt(0)
	s_barrier
	v_mfma_f32_16x16x32_bf16 v[86:89], v[138:141], v[194:197], v[86:89]
	v_mfma_f32_16x16x32_bf16 v[14:17], v[146:149], v[194:197], v[14:17]
	v_mfma_f32_16x16x32_bf16 v[70:73], v[138:141], v[202:205], v[70:73]
	v_mfma_f32_16x16x32_bf16 v[6:9], v[146:149], v[202:205], v[6:9]
	v_mfma_f32_16x16x32_bf16 v[102:105], v[138:141], v[228:231], v[102:105]
	v_mfma_f32_16x16x32_bf16 v[30:33], v[146:149], v[228:231], v[30:33]
	v_mfma_f32_16x16x32_bf16 v[98:101], v[138:141], v[236:239], v[98:101]
	v_mfma_f32_16x16x32_bf16 v[26:29], v[146:149], v[236:239], v[26:29]
	v_mfma_f32_16x16x32_bf16 v[86:89], v[142:145], v[198:201], v[86:89]
	v_mfma_f32_16x16x32_bf16 v[14:17], v[150:153], v[198:201], v[14:17]
	v_mfma_f32_16x16x32_bf16 v[70:73], v[142:145], v[214:217], v[70:73]
	v_mfma_f32_16x16x32_bf16 v[6:9], v[150:153], v[214:217], v[6:9]
	v_mfma_f32_16x16x32_bf16 v[102:105], v[142:145], v[232:235], v[102:105]
	v_mfma_f32_16x16x32_bf16 v[30:33], v[150:153], v[232:235], v[30:33]
	v_mfma_f32_16x16x32_bf16 v[98:101], v[142:145], v[240:243], v[98:101]
	v_mfma_f32_16x16x32_bf16 v[26:29], v[150:153], v[240:243], v[26:29]
	v_mfma_f32_16x16x32_bf16 v[82:85], v[154:157], v[194:197], v[82:85]
	v_mfma_f32_16x16x32_bf16 v[10:13], v[162:165], v[194:197], v[10:13]
	v_mfma_f32_16x16x32_bf16 v[66:69], v[154:157], v[202:205], v[66:69]
	v_mfma_f32_16x16x32_bf16 v[2:5], v[162:165], v[202:205], v[2:5]
	v_mfma_f32_16x16x32_bf16 v[94:97], v[154:157], v[228:231], v[94:97]
	v_mfma_f32_16x16x32_bf16 v[22:25], v[162:165], v[228:231], v[22:25]
	v_mfma_f32_16x16x32_bf16 v[90:93], v[154:157], v[236:239], v[90:93]
	v_mfma_f32_16x16x32_bf16 v[18:21], v[162:165], v[236:239], v[18:21]
	v_mfma_f32_16x16x32_bf16 v[82:85], v[158:161], v[198:201], v[82:85]
	v_mfma_f32_16x16x32_bf16 v[10:13], v[166:169], v[198:201], v[10:13]
	v_mfma_f32_16x16x32_bf16 v[66:69], v[158:161], v[214:217], v[66:69]
	v_mfma_f32_16x16x32_bf16 v[2:5], v[166:169], v[214:217], v[2:5]
	v_mfma_f32_16x16x32_bf16 v[94:97], v[158:161], v[232:235], v[94:97]
	v_mfma_f32_16x16x32_bf16 v[22:25], v[166:169], v[232:235], v[22:25]
	v_mfma_f32_16x16x32_bf16 v[90:93], v[158:161], v[240:243], v[90:93]
	v_mfma_f32_16x16x32_bf16 v[18:21], v[166:169], v[240:243], v[18:21]
	s_barrier
	s_add_u32 s35, s35, 0x100
	s_addc_u32 s51, s51, 0
	s_cmp_ge_i32 s52, s68
	s_mov_b64 s[48:49], s[14:15]
	s_mov_b32 s46, s52
	s_cbranch_scc0 .LBB0_1495
	s_movk_i32 s78, 0x7ff
	s_movk_i32 s76, 0x3000
	s_and_b64 vcc, exec, s[30:31]
	s_cbranch_vccz .LBB0_1470

; #define PG8_STAGE(bufoff, gbase, voff) do { _Pragma("unroll") for (int _i = 0; _i < 2; ++_i) \
;         __builtin_amdgcn_global_load_lds((const unsigned*)((const char*)(gbase) + (voff)[_i]), (PG8_LAS unsigned*)(lds + (bufoff) + ldsw + _i * 8192), 16, 0, 0); } while (0)
; #define PG8_LDA(dst, b, h) do { _Pragma("unroll") for (int m = 0; m < 4; ++m) _Pragma("unroll") for (int k = 0; k < 2; ++k) dst[m][k] = *(const PG8_LAS bf16x8*)(lds + PG8_SA(b, h) + aoff + m * 2048 + k * 1024); } while (0)
; #define PG8_LDB(dst, b, h) do { _Pragma("unroll") for (int n = 0; n < 2; ++n) _Pragma("unroll") for (int k = 0; k < 2; ++k) dst[n][k] = *(const PG8_LAS bf16x8*)(lds + PG8_SB(b, h) + boff + n * 2048 + k * 1024); } while (0)
; #define PG8_MMA(ai, bj, At, Bt) do { __builtin_amdgcn_s_setprio(1); _Pragma("unroll") for (int m = 0; m < 4; ++m) _Pragma("unroll") for (int n = 0; n < 2; ++n) _Pragma("unroll") for (int k = 0; k < 2; ++k) \
;         acc[ai][bj][m][n] = __builtin_amdgcn_mfma_f32_16x16x32_bf16(Bt[n][k], At[m][k], acc[ai][bj][m][n], 0, 0, 0); __builtin_amdgcn_s_setprio(0); } while (0)
; #define PG8_WAIT_V(n) asm volatile("s_waitcnt vmcnt(" #n ")" ::: "memory")
; #define PG8_WAIT_L(n) asm volatile("s_waitcnt lgkmcnt(" #n ")" ::: "memory")
; template <class Epi, class Sched, bool ALIGN_EPI = false, bool SP2 = false>
; __device__ __forceinline__ void gemm_phase(PG8_LAS unsigned char* lds, const Gemm g, const Sched& S, const Epi& E, const int wv) {
;     ...
;             const bool last = (t == nt - 2);
;             const char* a1 = cA + (size_t)(t + 1) * kstep;
;             const char* a2 = last ? nA : cA + (size_t)(t + 2) * kstep; const char* b2 = last ? nB : cB + (size_t)(t + 2) * kstep;
;             const char* a3 = a2 + kstep; const char* b3 = b2 + kstep;
;             if (last && has_next) S.a_ready(nxt);
;             if constexpr (SP2) {
;             PG8_LDB(B0, 0, 0); PG8_LDB(B1, 0, 1); PG8_SCHED; PG8_LDA(At, 0, 0); PG8_STAGE(PG8_SA(1, 1), a1 + hstepA, voffA);
;             PG8_WAIT_V(8); PG8_WAIT_L(0); PG8_BAR; PG8_MMA(0, 0, At, B0); PG8_MMA(0, 1, At, B1); PG8_BAR; PG8_SCHED;
;             PG8_LDA(At, 0, 1); PG8_STAGE(PG8_SB(0, 0), b2, voffB); PG8_STAGE(PG8_SB(0, 1), b2 + hstepB, voffB); PG8_STAGE(PG8_SA(0, 0), a2, voffA);
;             PG8_WAIT_V(8); PG8_WAIT_L(0); PG8_BAR; PG8_MMA(1, 0, At, B0); PG8_MMA(1, 1, At, B1); PG8_BAR; PG8_SCHED;
.LBB0_1676:
	s_add_i32 s67, s44, 2
	s_add_u32 s34, s30, 0x100
	s_addc_u32 s35, s31, 0
	s_add_i32 s70, 0, 0x10000
	s_cmp_eq_u32 s59, s44
	s_cselect_b32 s45, s13, s35
	s_cselect_b32 s44, s12, s34
	s_cselect_b32 s69, s15, s66
	s_cselect_b32 s68, s14, s65
	s_add_i32 s71, 0, 0x14000
	v_add_u32_e32 v142, s70, v230
	v_add_u32_e32 v158, s71, v230
	ds_read_b128 v[114:117], v142
	ds_read_b128 v[126:129], v142 offset:1024
	ds_read_b128 v[138:141], v142 offset:2048
	ds_read_b128 v[142:145], v142 offset:3072
	ds_read_b128 v[146:149], v158
	ds_read_b128 v[150:153], v158 offset:1024
	ds_read_b128 v[154:157], v158 offset:2048
	ds_read_b128 v[158:161], v158 offset:3072
	s_add_i32 m0, s52, 0xc000
	ds_read_b128 v[162:165], v235
	ds_read_b128 v[166:169], v235 offset:1024
	ds_read_b128 v[170:173], v235 offset:2048
	ds_read_b128 v[174:177], v235 offset:3072
	ds_read_b128 v[178:181], v235 offset:4096
	ds_read_b128 v[182:185], v235 offset:5120
	ds_read_b128 v[204:207], v235 offset:6144
	ds_read_b128 v[208:211], v235 offset:7168
	global_load_lds_dwordx4 v200, s[30:31]
	s_add_i32 m0, s52, 0xe000
	s_nop 0
	global_load_lds_dwordx4 v202, s[30:31]
	s_waitcnt vmcnt(8)
	s_waitcnt lgkmcnt(0)
	s_barrier
	v_mfma_f32_16x16x32_bf16 v[134:137], v[114:117], v[162:165], v[134:137]
	v_mfma_f32_16x16x32_bf16 v[130:133], v[138:141], v[162:165], v[130:133]
	v_mfma_f32_16x16x32_bf16 v[110:113], v[114:117], v[170:173], v[110:113]
	v_mfma_f32_16x16x32_bf16 v[106:109], v[138:141], v[170:173], v[106:109]
	v_mfma_f32_16x16x32_bf16 v[94:97], v[114:117], v[178:181], v[94:97]
	v_mfma_f32_16x16x32_bf16 v[90:93], v[138:141], v[178:181], v[90:93]
	v_mfma_f32_16x16x32_bf16 v[78:81], v[114:117], v[204:207], v[78:81]
	v_mfma_f32_16x16x32_bf16 v[74:77], v[138:141], v[204:207], v[74:77]
	v_mfma_f32_16x16x32_bf16 v[134:137], v[126:129], v[166:169], v[134:137]
	v_mfma_f32_16x16x32_bf16 v[130:133], v[142:145], v[166:169], v[130:133]
	v_mfma_f32_16x16x32_bf16 v[110:113], v[126:129], v[174:177], v[110:113]
	v_mfma_f32_16x16x32_bf16 v[106:109], v[142:145], v[174:177], v[106:109]
	v_mfma_f32_16x16x32_bf16 v[94:97], v[126:129], v[182:185], v[94:97]
	v_mfma_f32_16x16x32_bf16 v[90:93], v[142:145], v[182:185], v[90:93]
	v_mfma_f32_16x16x32_bf16 v[78:81], v[126:129], v[208:211], v[78:81]
	v_mfma_f32_16x16x32_bf16 v[74:77], v[142:145], v[208:211], v[74:77]
	v_mfma_f32_16x16x32_bf16 v[122:125], v[146:149], v[162:165], v[122:125]
	v_mfma_f32_16x16x32_bf16 v[118:121], v[154:157], v[162:165], v[118:121]
	v_mfma_f32_16x16x32_bf16 v[102:105], v[146:149], v[170:173], v[102:105]
	v_mfma_f32_16x16x32_bf16 v[98:101], v[154:157], v[170:173], v[98:101]
	v_mfma_f32_16x16x32_bf16 v[86:89], v[146:149], v[178:181], v[86:89]
	v_mfma_f32_16x16x32_bf16 v[82:85], v[154:157], v[178:181], v[82:85]
	v_mfma_f32_16x16x32_bf16 v[70:73], v[146:149], v[204:207], v[70:73]
	v_mfma_f32_16x16x32_bf16 v[66:69], v[154:157], v[204:207], v[66:69]
	v_mfma_f32_16x16x32_bf16 v[122:125], v[150:153], v[166:169], v[122:125]
	v_mfma_f32_16x16x32_bf16 v[118:121], v[158:161], v[166:169], v[118:121]
	v_mfma_f32_16x16x32_bf16 v[102:105], v[150:153], v[174:177], v[102:105]
	v_mfma_f32_16x16x32_bf16 v[98:101], v[158:161], v[174:177], v[98:101]
	v_mfma_f32_16x16x32_bf16 v[86:89], v[150:153], v[182:185], v[86:89]
	v_mfma_f32_16x16x32_bf16 v[82:85], v[158:161], v[182:185], v[82:85]
	v_mfma_f32_16x16x32_bf16 v[70:73], v[150:153], v[208:211], v[70:73]
	v_mfma_f32_16x16x32_bf16 v[66:69], v[158:161], v[208:211], v[66:69]
	s_barrier
	s_add_i32 s30, s70, s47
	v_lshl_add_u64 v[190:191], s[68:69], 0, v[0:1]
	s_mov_b32 m0, s30
	ds_read_b128 v[162:165], v235 offset:16384
	ds_read_b128 v[166:169], v235 offset:17408
	ds_read_b128 v[170:173], v235 offset:18432
	ds_read_b128 v[174:177], v235 offset:19456
	ds_read_b128 v[178:181], v235 offset:20480
	ds_read_b128 v[182:185], v235 offset:21504
	ds_read_b128 v[204:207], v235 offset:22528
	ds_read_b128 v[208:211], v235 offset:23552
	global_load_lds_dwordx4 v[190:191], off
	s_add_i32 m0, s30, 0x2000
	s_add_u32 s30, s68, s2
	v_lshl_add_u64 v[192:193], s[68:69], 0, v[198:199]
	s_addc_u32 s31, s69, s3
	s_add_i32 s68, s71, s47
	global_load_lds_dwordx4 v[192:193], off
	v_lshl_add_u64 v[212:213], s[30:31], 0, v[0:1]
	s_mov_b32 m0, s68
	v_lshl_add_u64 v[214:215], s[30:31], 0, v[198:199]
	global_load_lds_dwordx4 v[212:213], off
	s_add_i32 m0, s68, 0x2000
	global_load_lds_dwordx4 v[214:215], off
	s_mov_b32 m0, s52
	global_load_lds_dwordx4 v194, s[44:45]
	s_mov_b32 m0, s53
	s_nop 0
	global_load_lds_dwordx4 v196, s[44:45]
	s_waitcnt vmcnt(8)
	s_waitcnt lgkmcnt(0)
	s_barrier
; #define PG8_STAGE(bufoff, gbase, voff) do { _Pragma("unroll") for (int _i = 0; _i < 2; ++_i) \
;         __builtin_amdgcn_global_load_lds((const unsigned*)((const char*)(gbase) + (voff)[_i]), (PG8_LAS unsigned*)(lds + (bufoff) + ldsw + _i * 8192), 16, 0, 0); } while (0)
; #define PG8_LDA(dst, b, h) do { _Pragma("unroll") for (int m = 0; m < 4; ++m) _Pragma("unroll") for (int k = 0; k < 2; ++k) dst[m][k] = *(const PG8_LAS bf16x8*)(lds + PG8_SA(b, h) + aoff + m * 2048 + k * 1024); } while (0)
; #define PG8_LDB(dst, b, h) do { _Pragma("unroll") for (int n = 0; n < 2; ++n) _Pragma("unroll") for (int k = 0; k < 2; ++k) dst[n][k] = *(const PG8_LAS bf16x8*)(lds + PG8_SB(b, h) + boff + n * 2048 + k * 1024); } while (0)
; #define PG8_MMA(ai, bj, At, Bt) do { __builtin_amdgcn_s_setprio(1); _Pragma("unroll") for (int m = 0; m < 4; ++m) _Pragma("unroll") for (int n = 0; n < 2; ++n) _Pragma("unroll") for (int k = 0; k < 2; ++k) \
;         acc[ai][bj][m][n] = __builtin_amdgcn_mfma_f32_16x16x32_bf16(Bt[n][k], At[m][k], acc[ai][bj][m][n], 0, 0, 0); __builtin_amdgcn_s_setprio(0); } while (0)
; #define PG8_WAIT_V(n) asm volatile("s_waitcnt vmcnt(" #n ")" ::: "memory")
; #define PG8_WAIT_L(n) asm volatile("s_waitcnt lgkmcnt(" #n ")" ::: "memory")
; #define PG8_BAR __builtin_amdgcn_s_barrier()
; #define PG8_SCHED __builtin_amdgcn_sched_barrier(0)
; template <class Epi, class Sched, bool ALIGN_EPI = false, bool SP2 = false>
; __device__ __forceinline__ void gemm_phase(PG8_LAS unsigned char* lds, const Gemm g, const Sched& S, const Epi& E, const int wv) {
;     ...
;             PG8_WAIT_V(8); PG8_WAIT_L(0); PG8_BAR; PG8_MMA(1, 0, At, B0); PG8_MMA(1, 1, At, B1); PG8_BAR; PG8_SCHED;
;             PG8_LDB(B0, 1, 0); PG8_LDB(B1, 1, 1); PG8_SCHED; PG8_LDA(At, 1, 0); PG8_STAGE(PG8_SA(0, 1), a2 + hstepA, voffA);
;             PG8_WAIT_V(8); PG8_WAIT_L(0); PG8_BAR; PG8_MMA(0, 0, At, B0); PG8_MMA(0, 1, At, B1); PG8_BAR; PG8_SCHED;
	v_mfma_f32_16x16x32_bf16 v[62:65], v[114:117], v[162:165], v[62:65]
	v_mfma_f32_16x16x32_bf16 v[58:61], v[138:141], v[162:165], v[58:61]
	v_mfma_f32_16x16x32_bf16 v[46:49], v[114:117], v[170:173], v[46:49]
	v_mfma_f32_16x16x32_bf16 v[42:45], v[138:141], v[170:173], v[42:45]
	v_mfma_f32_16x16x32_bf16 v[30:33], v[114:117], v[178:181], v[30:33]
	v_mfma_f32_16x16x32_bf16 v[26:29], v[138:141], v[178:181], v[26:29]
	v_mfma_f32_16x16x32_bf16 v[14:17], v[114:117], v[204:207], v[14:17]
	v_mfma_f32_16x16x32_bf16 v[10:13], v[138:141], v[204:207], v[10:13]
	v_mfma_f32_16x16x32_bf16 v[62:65], v[126:129], v[166:169], v[62:65]
	v_mfma_f32_16x16x32_bf16 v[58:61], v[142:145], v[166:169], v[58:61]
	v_mfma_f32_16x16x32_bf16 v[46:49], v[126:129], v[174:177], v[46:49]
	v_mfma_f32_16x16x32_bf16 v[42:45], v[142:145], v[174:177], v[42:45]
	v_mfma_f32_16x16x32_bf16 v[30:33], v[126:129], v[182:185], v[30:33]
	v_mfma_f32_16x16x32_bf16 v[26:29], v[142:145], v[182:185], v[26:29]
	v_mfma_f32_16x16x32_bf16 v[14:17], v[126:129], v[208:211], v[14:17]
	v_mfma_f32_16x16x32_bf16 v[10:13], v[142:145], v[208:211], v[10:13]
	v_mfma_f32_16x16x32_bf16 v[54:57], v[146:149], v[162:165], v[54:57]
	v_mfma_f32_16x16x32_bf16 v[50:53], v[154:157], v[162:165], v[50:53]
	v_mfma_f32_16x16x32_bf16 v[38:41], v[146:149], v[170:173], v[38:41]
	v_mfma_f32_16x16x32_bf16 v[34:37], v[154:157], v[170:173], v[34:37]
	v_mfma_f32_16x16x32_bf16 v[22:25], v[146:149], v[178:181], v[22:25]
	v_mfma_f32_16x16x32_bf16 v[18:21], v[154:157], v[178:181], v[18:21]
	v_mfma_f32_16x16x32_bf16 v[6:9], v[146:149], v[204:207], v[6:9]
	v_mfma_f32_16x16x32_bf16 v[2:5], v[154:157], v[204:207], v[2:5]
	v_mfma_f32_16x16x32_bf16 v[54:57], v[150:153], v[166:169], v[54:57]
	v_mfma_f32_16x16x32_bf16 v[50:53], v[158:161], v[166:169], v[50:53]
	v_mfma_f32_16x16x32_bf16 v[38:41], v[150:153], v[174:177], v[38:41]
	v_mfma_f32_16x16x32_bf16 v[34:37], v[158:161], v[174:177], v[34:37]
	v_mfma_f32_16x16x32_bf16 v[22:25], v[150:153], v[182:185], v[22:25]
	v_mfma_f32_16x16x32_bf16 v[18:21], v[158:161], v[182:185], v[18:21]
	v_mfma_f32_16x16x32_bf16 v[6:9], v[150:153], v[208:211], v[6:9]
	v_mfma_f32_16x16x32_bf16 v[2:5], v[158:161], v[208:211], v[2:5]
	s_barrier
	s_add_i32 s68, 0, 0x18000
	s_add_i32 s69, 0, 0x1c000
	v_add_u32_e32 v142, s68, v230
	v_add_u32_e32 v158, s69, v230
	ds_read_b128 v[114:117], v142
	ds_read_b128 v[126:129], v142 offset:1024
	ds_read_b128 v[138:141], v142 offset:2048
	ds_read_b128 v[142:145], v142 offset:3072
	ds_read_b128 v[146:149], v158
	ds_read_b128 v[150:153], v158 offset:1024
	ds_read_b128 v[154:157], v158 offset:2048
	ds_read_b128 v[158:161], v158 offset:3072
	s_add_u32 s30, s44, 0x180000
	s_addc_u32 s31, s45, 0
	s_mov_b32 m0, s54
	ds_read_b128 v[162:165], v235 offset:32768
	ds_read_b128 v[166:169], v235 offset:33792
	ds_read_b128 v[170:173], v235 offset:34816
	ds_read_b128 v[174:177], v235 offset:35840
	ds_read_b128 v[178:181], v235 offset:36864
	ds_read_b128 v[182:185], v235 offset:37888
	ds_read_b128 v[204:207], v235 offset:38912
	ds_read_b128 v[208:211], v235 offset:39936
	global_load_lds_dwordx4 v194, s[30:31]
	s_mov_b32 m0, s55
	s_nop 0
	global_load_lds_dwordx4 v196, s[30:31]
	s_waitcnt vmcnt(8)
	s_waitcnt lgkmcnt(0)
	s_barrier
	v_mfma_f32_16x16x32_bf16 v[134:137], v[114:117], v[162:165], v[134:137]
	v_mfma_f32_16x16x32_bf16 v[130:133], v[138:141], v[162:165], v[130:133]
	v_mfma_f32_16x16x32_bf16 v[110:113], v[114:117], v[170:173], v[110:113]
	v_mfma_f32_16x16x32_bf16 v[106:109], v[138:141], v[170:173], v[106:109]
	v_mfma_f32_16x16x32_bf16 v[94:97], v[114:117], v[178:181], v[94:97]
	v_mfma_f32_16x16x32_bf16 v[90:93], v[138:141], v[178:181], v[90:93]
	v_mfma_f32_16x16x32_bf16 v[78:81], v[114:117], v[204:207], v[78:81]
	v_mfma_f32_16x16x32_bf16 v[74:77], v[138:141], v[204:207], v[74:77]
	v_mfma_f32_16x16x32_bf16 v[134:137], v[126:129], v[166:169], v[134:137]
	v_mfma_f32_16x16x32_bf16 v[130:133], v[142:145], v[166:169], v[130:133]
	v_mfma_f32_16x16x32_bf16 v[110:113], v[126:129], v[174:177], v[110:113]
	v_mfma_f32_16x16x32_bf16 v[106:109], v[142:145], v[174:177], v[106:109]
	v_mfma_f32_16x16x32_bf16 v[94:97], v[126:129], v[182:185], v[94:97]
	v_mfma_f32_16x16x32_bf16 v[90:93], v[142:145], v[182:185], v[90:93]
	v_mfma_f32_16x16x32_bf16 v[78:81], v[126:129], v[208:211], v[78:81]
	v_mfma_f32_16x16x32_bf16 v[74:77], v[142:145], v[208:211], v[74:77]
	v_mfma_f32_16x16x32_bf16 v[122:125], v[146:149], v[162:165], v[122:125]
	v_mfma_f32_16x16x32_bf16 v[118:121], v[154:157], v[162:165], v[118:121]
	v_mfma_f32_16x16x32_bf16 v[102:105], v[146:149], v[170:173], v[102:105]
	v_mfma_f32_16x16x32_bf16 v[98:101], v[154:157], v[170:173], v[98:101]
	v_mfma_f32_16x16x32_bf16 v[86:89], v[146:149], v[178:181], v[86:89]
	v_mfma_f32_16x16x32_bf16 v[82:85], v[154:157], v[178:181], v[82:85]
	v_mfma_f32_16x16x32_bf16 v[70:73], v[146:149], v[204:207], v[70:73]
	v_mfma_f32_16x16x32_bf16 v[66:69], v[154:157], v[204:207], v[66:69]
	v_mfma_f32_16x16x32_bf16 v[122:125], v[150:153], v[166:169], v[122:125]
	v_mfma_f32_16x16x32_bf16 v[118:121], v[158:161], v[166:169], v[118:121]
	v_mfma_f32_16x16x32_bf16 v[102:105], v[150:153], v[174:177], v[102:105]
	v_mfma_f32_16x16x32_bf16 v[98:101], v[158:161], v[174:177], v[98:101]
	v_mfma_f32_16x16x32_bf16 v[86:89], v[150:153], v[182:185], v[86:89]
	v_mfma_f32_16x16x32_bf16 v[82:85], v[158:161], v[182:185], v[82:85]
	v_mfma_f32_16x16x32_bf16 v[70:73], v[150:153], v[208:211], v[70:73]
	v_mfma_f32_16x16x32_bf16 v[66:69], v[158:161], v[208:211], v[66:69]
	s_barrier
; #define PG8_STAGE(bufoff, gbase, voff) do { _Pragma("unroll") for (int _i = 0; _i < 2; ++_i) \
;         __builtin_amdgcn_global_load_lds((const unsigned*)((const char*)(gbase) + (voff)[_i]), (PG8_LAS unsigned*)(lds + (bufoff) + ldsw + _i * 8192), 16, 0, 0); } while (0)
; #define PG8_LDA(dst, b, h) do { _Pragma("unroll") for (int m = 0; m < 4; ++m) _Pragma("unroll") for (int k = 0; k < 2; ++k) dst[m][k] = *(const PG8_LAS bf16x8*)(lds + PG8_SA(b, h) + aoff + m * 2048 + k * 1024); } while (0)
; #define PG8_MMA(ai, bj, At, Bt) do { __builtin_amdgcn_s_setprio(1); _Pragma("unroll") for (int m = 0; m < 4; ++m) _Pragma("unroll") for (int n = 0; n < 2; ++n) _Pragma("unroll") for (int k = 0; k < 2; ++k) \
;         acc[ai][bj][m][n] = __builtin_amdgcn_mfma_f32_16x16x32_bf16(Bt[n][k], At[m][k], acc[ai][bj][m][n], 0, 0, 0); __builtin_amdgcn_s_setprio(0); } while (0)
; #define PG8_WAIT_V(n) asm volatile("s_waitcnt vmcnt(" #n ")" ::: "memory")
; #define PG8_WAIT_L(n) asm volatile("s_waitcnt lgkmcnt(" #n ")" ::: "memory")
; #define PG8_BAR __builtin_amdgcn_s_barrier()
; #define PG8_SCHED __builtin_amdgcn_sched_barrier(0)
; template <class Epi, class Sched, bool ALIGN_EPI = false, bool SP2 = false>
; __device__ __forceinline__ void gemm_phase(PG8_LAS unsigned char* lds, const Gemm g, const Sched& S, const Epi& E, const int wv) {
;     ...
;             PG8_LDA(At, 1, 1); PG8_STAGE(PG8_SB(1, 0), b3, voffB); PG8_STAGE(PG8_SB(1, 1), b3 + hstepB, voffB); PG8_STAGE(PG8_SA(1, 0), a3, voffA);
;             PG8_WAIT_V(8); PG8_WAIT_L(0); PG8_BAR; PG8_MMA(1, 0, At, B0); PG8_MMA(1, 1, At, B1); PG8_BAR; PG8_SCHED;
	s_add_i32 s30, s68, s47
	s_add_i32 m0, s30, 0xffffff80
	ds_read_b128 v[162:165], v235 offset:49152
	ds_read_b128 v[166:169], v235 offset:50176
	ds_read_b128 v[170:173], v235 offset:51200
	ds_read_b128 v[174:177], v235 offset:52224
	ds_read_b128 v[178:181], v235 offset:53248
	ds_read_b128 v[182:185], v235 offset:54272
	ds_read_b128 v[204:207], v235 offset:55296
	ds_read_b128 v[208:211], v235 offset:56320
	global_load_lds_dwordx4 v[190:191], off offset:128
	s_add_i32 m0, s30, 0x1f80
	s_add_i32 s30, s69, s47
	global_load_lds_dwordx4 v[192:193], off offset:128
	s_add_i32 m0, s30, 0xffffff80
	s_nop 0
	global_load_lds_dwordx4 v[212:213], off offset:128
	s_add_i32 m0, s30, 0x1f80
	s_nop 0
	global_load_lds_dwordx4 v[214:215], off offset:128
	s_add_i32 m0, s57, 0xffffff80
	s_nop 0
	global_load_lds_dwordx4 v194, s[44:45] offset:128
	s_add_i32 m0, s58, 0xffffff80
	s_nop 0
	global_load_lds_dwordx4 v196, s[44:45] offset:128
	s_waitcnt vmcnt(8)
	s_waitcnt lgkmcnt(0)
	s_barrier
	v_mfma_f32_16x16x32_bf16 v[62:65], v[114:117], v[162:165], v[62:65]
	v_mfma_f32_16x16x32_bf16 v[58:61], v[138:141], v[162:165], v[58:61]
	v_mfma_f32_16x16x32_bf16 v[46:49], v[114:117], v[170:173], v[46:49]
	v_mfma_f32_16x16x32_bf16 v[42:45], v[138:141], v[170:173], v[42:45]
	v_mfma_f32_16x16x32_bf16 v[30:33], v[114:117], v[178:181], v[30:33]
	v_mfma_f32_16x16x32_bf16 v[26:29], v[138:141], v[178:181], v[26:29]
	v_mfma_f32_16x16x32_bf16 v[14:17], v[114:117], v[204:207], v[14:17]
	v_mfma_f32_16x16x32_bf16 v[10:13], v[138:141], v[204:207], v[10:13]
	v_mfma_f32_16x16x32_bf16 v[62:65], v[126:129], v[166:169], v[62:65]
	v_mfma_f32_16x16x32_bf16 v[58:61], v[142:145], v[166:169], v[58:61]
	v_mfma_f32_16x16x32_bf16 v[46:49], v[126:129], v[174:177], v[46:49]
	v_mfma_f32_16x16x32_bf16 v[42:45], v[142:145], v[174:177], v[42:45]
	v_mfma_f32_16x16x32_bf16 v[30:33], v[126:129], v[182:185], v[30:33]
	v_mfma_f32_16x16x32_bf16 v[26:29], v[142:145], v[182:185], v[26:29]
	v_mfma_f32_16x16x32_bf16 v[14:17], v[126:129], v[208:211], v[14:17]
	v_mfma_f32_16x16x32_bf16 v[10:13], v[142:145], v[208:211], v[10:13]
	v_mfma_f32_16x16x32_bf16 v[54:57], v[146:149], v[162:165], v[54:57]
	v_mfma_f32_16x16x32_bf16 v[50:53], v[154:157], v[162:165], v[50:53]
	v_mfma_f32_16x16x32_bf16 v[38:41], v[146:149], v[170:173], v[38:41]
	v_mfma_f32_16x16x32_bf16 v[34:37], v[154:157], v[170:173], v[34:37]
	v_mfma_f32_16x16x32_bf16 v[22:25], v[146:149], v[178:181], v[22:25]
	v_mfma_f32_16x16x32_bf16 v[18:21], v[154:157], v[178:181], v[18:21]
	v_mfma_f32_16x16x32_bf16 v[6:9], v[146:149], v[204:207], v[6:9]
	v_mfma_f32_16x16x32_bf16 v[2:5], v[154:157], v[204:207], v[2:5]
	v_mfma_f32_16x16x32_bf16 v[54:57], v[150:153], v[166:169], v[54:57]
	v_mfma_f32_16x16x32_bf16 v[50:53], v[158:161], v[166:169], v[50:53]
	v_mfma_f32_16x16x32_bf16 v[38:41], v[150:153], v[174:177], v[38:41]
	v_mfma_f32_16x16x32_bf16 v[34:37], v[158:161], v[174:177], v[34:37]
	v_mfma_f32_16x16x32_bf16 v[22:25], v[150:153], v[182:185], v[22:25]
	v_mfma_f32_16x16x32_bf16 v[18:21], v[158:161], v[182:185], v[18:21]
	v_mfma_f32_16x16x32_bf16 v[6:9], v[150:153], v[208:211], v[6:9]
	v_mfma_f32_16x16x32_bf16 v[2:5], v[158:161], v[208:211], v[2:5]
	s_barrier
	s_add_u32 s65, s65, 0x100
	s_addc_u32 s66, s66, 0
	s_cmp_ge_i32 s67, s56
	s_mov_b64 s[30:31], s[34:35]
	s_mov_b32 s44, s67
	s_cbranch_scc0 .LBB0_1676
	s_movk_i32 s68, 0x4000
	s_movk_i32 s69, 0x6000
	s_mov_b32 s70, 0x18000
	s_mov_b32 s71, 0x3f317217
	s_and_b64 vcc, exec, s[28:29]
	s_cbranch_vccz .LBB0_1652
